# diff-attention tail half-steps issue all LDS fragment reads up front; redundant mid-block s_setprio 0/1 pairs removed from GEMM MFMA blocks
# baseline (speedup 1.0000x reference)
; #define PG8_STAGE(bufoff, gbase, voff) do { _Pragma("unroll") for (int _i = 0; _i < 2; ++_i) \
;         __builtin_amdgcn_global_load_lds((const unsigned*)((const char*)(gbase) + (voff)[_i]), (PG8_LAS unsigned*)(lds + (bufoff) + ldsw + _i * 8192), 16, 0, 0); } while (0)
; #define PG8_LDA(dst, b, h) do { _Pragma("unroll") for (int m = 0; m < 4; ++m) _Pragma("unroll") for (int k = 0; k < 2; ++k) dst[m][k] = *(const PG8_LAS bf16x8*)(lds + PG8_SA(b, h) + aoff + m * 2048 + k * 1024); } while (0)
; #define PG8_LDB(dst, b, h) do { _Pragma("unroll") for (int n = 0; n < 2; ++n) _Pragma("unroll") for (int k = 0; k < 2; ++k) dst[n][k] = *(const PG8_LAS bf16x8*)(lds + PG8_SB(b, h) + boff + n * 2048 + k * 1024); } while (0)
; #define PG8_MMA(ai, bj, At, Bt) do { __builtin_amdgcn_s_setprio(1); _Pragma("unroll") for (int m = 0; m < 4; ++m) _Pragma("unroll") for (int n = 0; n < 2; ++n) _Pragma("unroll") for (int k = 0; k < 2; ++k) \
;         acc[ai][bj][m][n] = __builtin_amdgcn_mfma_f32_16x16x32_bf16(Bt[n][k], At[m][k], acc[ai][bj][m][n], 0, 0, 0); __builtin_amdgcn_s_setprio(0); } while (0)
; #define PG8_WAIT_V(n) asm volatile("s_waitcnt vmcnt(" #n ")" ::: "memory")
; #define PG8_WAIT_L(n) asm volatile("s_waitcnt lgkmcnt(" #n ")" ::: "memory")
; template <class Epi, class Sched, bool ALIGN_EPI = false, bool SP2 = false>
; __device__ __forceinline__ void gemm_phase(PG8_LAS unsigned char* lds, const Gemm g, const Sched& S, const Epi& E) {
;     ...
;             const bool last = (t == nt - 2);
;             const char* a1 = cA + (size_t)(t + 1) * kstep;
;             const char* a2 = last ? nA : cA + (size_t)(t + 2) * kstep; const char* b2 = last ? nB : cB + (size_t)(t + 2) * kstep;
;             const char* a3 = a2 + kstep; const char* b3 = b2 + kstep;
;             if (last && has_next) S.a_ready(nxt);
;             if constexpr (SP2) {
;             PG8_LDB(B0, 0, 0); PG8_LDB(B1, 0, 1); PG8_SCHED; PG8_LDA(At, 0, 0); PG8_STAGE(PG8_SA(1, 1), a1 + hstep, voffA);
;             PG8_WAIT_V(8); PG8_WAIT_L(0); PG8_BAR; PG8_MMA(0, 0, At, B0); PG8_MMA(0, 1, At, B1); PG8_BAR; PG8_SCHED;
;             PG8_LDA(At, 0, 1); PG8_STAGE(PG8_SB(0, 0), b2, voffB); PG8_STAGE(PG8_SB(0, 1), b2 + hstep, voffB); PG8_STAGE(PG8_SA(0, 0), a2, voffA);
;             PG8_WAIT_V(8); PG8_WAIT_L(0); PG8_BAR; PG8_MMA(1, 0, At, B0); PG8_MMA(1, 1, At, B1); PG8_BAR; PG8_SCHED;
.LBB0_244:
	ds_read_b128 v[128:131], v169
	ds_read_b128 v[156:159], v169 offset:1024
	ds_read_b128 v[160:163], v169 offset:2048
	ds_read_b128 v[164:167], v169 offset:3072
	ds_read_b128 v[176:179], v170
	ds_read_b128 v[180:183], v170 offset:1024
	ds_read_b128 v[188:191], v170 offset:2048
	ds_read_b128 v[192:195], v170 offset:3072
	s_add_u32 s0, s4, 0xfff80080
	s_addc_u32 s1, s5, -1
	s_cmp_eq_u32 vcc_hi, 28
	s_cselect_b32 s9, s41, s1
	s_cselect_b32 s8, s51, s0
	s_cselect_b32 s7, s43, vcc_lo
	s_cselect_b32 s6, s56, s57
	s_add_i32 m0, s49, 0xc000
	ds_read_b128 v[196:199], v171
	ds_read_b128 v[200:203], v171 offset:1024
	ds_read_b128 v[204:207], v171 offset:2048
	ds_read_b128 v[208:211], v171 offset:3072
	ds_read_b128 v[212:215], v171 offset:4096
	ds_read_b128 v[216:219], v171 offset:5120
	ds_read_b128 v[220:223], v171 offset:6144
	ds_read_b128 v[224:227], v171 offset:7168
	global_load_lds_dwordx4 v144, s[4:5]
	s_add_i32 m0, s49, 0xe000
	s_nop 0
	global_load_lds_dwordx4 v146, s[4:5]
	s_waitcnt vmcnt(8)
	s_waitcnt lgkmcnt(0)
	s_barrier
	s_setprio 1
	s_waitcnt lgkmcnt(0)
	v_mfma_f32_16x16x32_bf16 v[124:127], v[128:131], v[196:199], v[124:127]
	v_mfma_f32_16x16x32_bf16 v[120:123], v[160:163], v[196:199], v[120:123]
	v_mfma_f32_16x16x32_bf16 v[108:111], v[128:131], v[204:207], v[108:111]
	v_mfma_f32_16x16x32_bf16 v[104:107], v[160:163], v[204:207], v[104:107]
	v_mfma_f32_16x16x32_bf16 v[92:95], v[128:131], v[212:215], v[92:95]
	v_mfma_f32_16x16x32_bf16 v[88:91], v[160:163], v[212:215], v[88:91]
	v_mfma_f32_16x16x32_bf16 v[76:79], v[128:131], v[220:223], v[76:79]
	v_mfma_f32_16x16x32_bf16 v[72:75], v[160:163], v[220:223], v[72:75]
	v_mfma_f32_16x16x32_bf16 v[124:127], v[156:159], v[200:203], v[124:127]
	v_mfma_f32_16x16x32_bf16 v[120:123], v[164:167], v[200:203], v[120:123]
	v_mfma_f32_16x16x32_bf16 v[108:111], v[156:159], v[208:211], v[108:111]
	v_mfma_f32_16x16x32_bf16 v[104:107], v[164:167], v[208:211], v[104:107]
	v_mfma_f32_16x16x32_bf16 v[92:95], v[156:159], v[216:219], v[92:95]
	v_mfma_f32_16x16x32_bf16 v[88:91], v[164:167], v[216:219], v[88:91]
	v_mfma_f32_16x16x32_bf16 v[76:79], v[156:159], v[224:227], v[76:79]
	v_mfma_f32_16x16x32_bf16 v[72:75], v[164:167], v[224:227], v[72:75]
	v_mfma_f32_16x16x32_bf16 v[116:119], v[176:179], v[196:199], v[116:119]
	v_mfma_f32_16x16x32_bf16 v[112:115], v[188:191], v[196:199], v[112:115]
	v_mfma_f32_16x16x32_bf16 v[100:103], v[176:179], v[204:207], v[100:103]
	v_mfma_f32_16x16x32_bf16 v[96:99], v[188:191], v[204:207], v[96:99]
	v_mfma_f32_16x16x32_bf16 v[84:87], v[176:179], v[212:215], v[84:87]
	v_mfma_f32_16x16x32_bf16 v[80:83], v[188:191], v[212:215], v[80:83]
	v_mfma_f32_16x16x32_bf16 v[68:71], v[176:179], v[220:223], v[68:71]
	v_mfma_f32_16x16x32_bf16 v[64:67], v[188:191], v[220:223], v[64:67]
	v_mfma_f32_16x16x32_bf16 v[116:119], v[180:183], v[200:203], v[116:119]
	v_mfma_f32_16x16x32_bf16 v[112:115], v[192:195], v[200:203], v[112:115]
	v_mfma_f32_16x16x32_bf16 v[100:103], v[180:183], v[208:211], v[100:103]
	v_mfma_f32_16x16x32_bf16 v[96:99], v[192:195], v[208:211], v[96:99]
	v_mfma_f32_16x16x32_bf16 v[84:87], v[180:183], v[216:219], v[84:87]
	v_mfma_f32_16x16x32_bf16 v[80:83], v[192:195], v[216:219], v[80:83]
	v_mfma_f32_16x16x32_bf16 v[68:71], v[180:183], v[224:227], v[68:71]
	v_mfma_f32_16x16x32_bf16 v[64:67], v[192:195], v[224:227], v[64:67]
	s_setprio 0
	s_barrier
	s_add_u32 s98, s6, s26
	s_addc_u32 s99, s7, s27
	s_add_u32 s100, s8, s26
	s_addc_u32 s101, s9, s27
	s_add_i32 s0, s70, s58
	s_mov_b32 m0, s0
	ds_read_b128 v[196:199], v171 offset:16384
	ds_read_b128 v[200:203], v171 offset:17408
	ds_read_b128 v[204:207], v171 offset:18432
	ds_read_b128 v[208:211], v171 offset:19456
	ds_read_b128 v[212:215], v171 offset:20480
	ds_read_b128 v[216:219], v171 offset:21504
	ds_read_b128 v[220:223], v171 offset:22528
	ds_read_b128 v[224:227], v171 offset:23552
	global_load_lds_dwordx4 v136, s[6:7]
	s_add_i32 m0, s0, 0x2000
	s_add_u32 s0, s6, 0x80000
	s_addc_u32 s1, s7, 0
	s_add_i32 s83, s72, s58
	global_load_lds_dwordx4 v140, s[6:7]
	s_mov_b32 m0, s83
	s_nop 0
	global_load_lds_dwordx4 v136, s[0:1]
	s_add_i32 m0, s83, 0x2000
	s_nop 0
	global_load_lds_dwordx4 v140, s[0:1]
	s_mov_b32 m0, s49
	s_nop 0
	global_load_lds_dwordx4 v134, s[8:9]
	s_mov_b32 m0, s59
	s_nop 0
	global_load_lds_dwordx4 v138, s[8:9]
	s_waitcnt vmcnt(8)
	s_waitcnt lgkmcnt(0)
	s_barrier
	s_setprio 1
	s_waitcnt lgkmcnt(0)
	v_mfma_f32_16x16x32_bf16 v[60:63], v[128:131], v[196:199], v[60:63]
	v_mfma_f32_16x16x32_bf16 v[56:59], v[160:163], v[196:199], v[56:59]
	v_mfma_f32_16x16x32_bf16 v[44:47], v[128:131], v[204:207], v[44:47]
	v_mfma_f32_16x16x32_bf16 v[40:43], v[160:163], v[204:207], v[40:43]
	v_mfma_f32_16x16x32_bf16 v[28:31], v[128:131], v[212:215], v[28:31]
	v_mfma_f32_16x16x32_bf16 v[24:27], v[160:163], v[212:215], v[24:27]
	v_mfma_f32_16x16x32_bf16 v[12:15], v[128:131], v[220:223], v[12:15]
	v_mfma_f32_16x16x32_bf16 v[8:11], v[160:163], v[220:223], v[8:11]
	v_mfma_f32_16x16x32_bf16 v[60:63], v[156:159], v[200:203], v[60:63]
	v_mfma_f32_16x16x32_bf16 v[56:59], v[164:167], v[200:203], v[56:59]
	v_mfma_f32_16x16x32_bf16 v[44:47], v[156:159], v[208:211], v[44:47]
	v_mfma_f32_16x16x32_bf16 v[40:43], v[164:167], v[208:211], v[40:43]
	v_mfma_f32_16x16x32_bf16 v[28:31], v[156:159], v[216:219], v[28:31]
	v_mfma_f32_16x16x32_bf16 v[24:27], v[164:167], v[216:219], v[24:27]
	v_mfma_f32_16x16x32_bf16 v[12:15], v[156:159], v[224:227], v[12:15]
	v_mfma_f32_16x16x32_bf16 v[8:11], v[164:167], v[224:227], v[8:11]
	v_mfma_f32_16x16x32_bf16 v[52:55], v[176:179], v[196:199], v[52:55]
	v_mfma_f32_16x16x32_bf16 v[48:51], v[188:191], v[196:199], v[48:51]
	v_mfma_f32_16x16x32_bf16 v[36:39], v[176:179], v[204:207], v[36:39]
	v_mfma_f32_16x16x32_bf16 v[32:35], v[188:191], v[204:207], v[32:35]
	v_mfma_f32_16x16x32_bf16 v[20:23], v[176:179], v[212:215], v[20:23]
	v_mfma_f32_16x16x32_bf16 v[16:19], v[188:191], v[212:215], v[16:19]
	v_mfma_f32_16x16x32_bf16 v[4:7], v[176:179], v[220:223], v[4:7]
	v_mfma_f32_16x16x32_bf16 v[0:3], v[188:191], v[220:223], v[0:3]
	v_mfma_f32_16x16x32_bf16 v[52:55], v[180:183], v[200:203], v[52:55]
	v_mfma_f32_16x16x32_bf16 v[48:51], v[192:195], v[200:203], v[48:51]
	v_mfma_f32_16x16x32_bf16 v[36:39], v[180:183], v[208:211], v[36:39]
	v_mfma_f32_16x16x32_bf16 v[32:35], v[192:195], v[208:211], v[32:35]
	v_mfma_f32_16x16x32_bf16 v[20:23], v[180:183], v[216:219], v[20:23]
	v_mfma_f32_16x16x32_bf16 v[16:19], v[192:195], v[216:219], v[16:19]
	v_mfma_f32_16x16x32_bf16 v[4:7], v[180:183], v[224:227], v[4:7]
	v_mfma_f32_16x16x32_bf16 v[0:3], v[192:195], v[224:227], v[0:3]
	s_setprio 0
	s_barrier
; #define PG8_STAGE(bufoff, gbase, voff) do { _Pragma("unroll") for (int _i = 0; _i < 2; ++_i) \
;         __builtin_amdgcn_global_load_lds((const unsigned*)((const char*)(gbase) + (voff)[_i]), (PG8_LAS unsigned*)(lds + (bufoff) + ldsw + _i * 8192), 16, 0, 0); } while (0)
; #define PG8_LDA(dst, b, h) do { _Pragma("unroll") for (int m = 0; m < 4; ++m) _Pragma("unroll") for (int k = 0; k < 2; ++k) dst[m][k] = *(const PG8_LAS bf16x8*)(lds + PG8_SA(b, h) + aoff + m * 2048 + k * 1024); } while (0)
; #define PG8_LDB(dst, b, h) do { _Pragma("unroll") for (int n = 0; n < 2; ++n) _Pragma("unroll") for (int k = 0; k < 2; ++k) dst[n][k] = *(const PG8_LAS bf16x8*)(lds + PG8_SB(b, h) + boff + n * 2048 + k * 1024); } while (0)
; #define PG8_MMA(ai, bj, At, Bt) do { __builtin_amdgcn_s_setprio(1); _Pragma("unroll") for (int m = 0; m < 4; ++m) _Pragma("unroll") for (int n = 0; n < 2; ++n) _Pragma("unroll") for (int k = 0; k < 2; ++k) \
;         acc[ai][bj][m][n] = __builtin_amdgcn_mfma_f32_16x16x32_bf16(Bt[n][k], At[m][k], acc[ai][bj][m][n], 0, 0, 0); __builtin_amdgcn_s_setprio(0); } while (0)
; #define PG8_WAIT_V(n) asm volatile("s_waitcnt vmcnt(" #n ")" ::: "memory")
; #define PG8_WAIT_L(n) asm volatile("s_waitcnt lgkmcnt(" #n ")" ::: "memory")
; #define PG8_BAR __builtin_amdgcn_s_barrier()
; #define PG8_SCHED __builtin_amdgcn_sched_barrier(0)
; template <class Epi, class Sched, bool ALIGN_EPI = false, bool SP2 = false>
; __device__ __forceinline__ void gemm_phase(PG8_LAS unsigned char* lds, const Gemm g, const Sched& S, const Epi& E) {
;     ...
;             PG8_LDB(B0, 1, 0); PG8_LDB(B1, 1, 1); PG8_SCHED; PG8_LDA(At, 1, 0); PG8_STAGE(PG8_SA(0, 1), a2 + hstep, voffA);
;             PG8_WAIT_V(8); PG8_WAIT_L(0); PG8_BAR; PG8_MMA(0, 0, At, B0); PG8_MMA(0, 1, At, B1); PG8_BAR; PG8_SCHED;
;             PG8_LDA(At, 1, 1); PG8_STAGE(PG8_SB(1, 0), b3, voffB); PG8_STAGE(PG8_SB(1, 1), b3 + hstep, voffB); PG8_STAGE(PG8_SA(1, 0), a3, voffA);
;             PG8_WAIT_V(8); PG8_WAIT_L(0); PG8_BAR; PG8_MMA(1, 0, At, B0); PG8_MMA(1, 1, At, B1); PG8_BAR; PG8_SCHED;
	s_add_i32 s83, 0, 0x18000
	v_add_u32_e32 v142, s83, v168
	s_add_i32 s88, 0, 0x1c000
	ds_read_b128 v[128:131], v142
	ds_read_b128 v[156:159], v142 offset:1024
	ds_read_b128 v[160:163], v142 offset:2048
	ds_read_b128 v[164:167], v142 offset:3072
	v_add_u32_e32 v142, s88, v168
	ds_read_b128 v[176:179], v142
	ds_read_b128 v[180:183], v142 offset:1024
	ds_read_b128 v[188:191], v142 offset:2048
	ds_read_b128 v[192:195], v142 offset:3072
	s_add_u32 s0, s8, 0x80000
	s_addc_u32 s1, s9, 0
	s_mov_b32 m0, s73
	ds_read_b128 v[196:199], v171 offset:32768
	ds_read_b128 v[200:203], v171 offset:33792
	ds_read_b128 v[204:207], v171 offset:34816
	ds_read_b128 v[208:211], v171 offset:35840
	ds_read_b128 v[212:215], v171 offset:36864
	ds_read_b128 v[216:219], v171 offset:37888
	ds_read_b128 v[220:223], v171 offset:38912
	ds_read_b128 v[224:227], v171 offset:39936
	global_load_lds_dwordx4 v134, s[0:1]
	s_mov_b32 m0, s74
	s_nop 0
	global_load_lds_dwordx4 v138, s[0:1]
	s_waitcnt vmcnt(8)
	s_waitcnt lgkmcnt(0)
	s_barrier
	s_setprio 1
	s_waitcnt lgkmcnt(0)
	v_mfma_f32_16x16x32_bf16 v[124:127], v[128:131], v[196:199], v[124:127]
	v_mfma_f32_16x16x32_bf16 v[120:123], v[160:163], v[196:199], v[120:123]
	v_mfma_f32_16x16x32_bf16 v[108:111], v[128:131], v[204:207], v[108:111]
	v_mfma_f32_16x16x32_bf16 v[104:107], v[160:163], v[204:207], v[104:107]
	v_mfma_f32_16x16x32_bf16 v[92:95], v[128:131], v[212:215], v[92:95]
	v_mfma_f32_16x16x32_bf16 v[88:91], v[160:163], v[212:215], v[88:91]
	v_mfma_f32_16x16x32_bf16 v[76:79], v[128:131], v[220:223], v[76:79]
	v_mfma_f32_16x16x32_bf16 v[72:75], v[160:163], v[220:223], v[72:75]
	v_mfma_f32_16x16x32_bf16 v[124:127], v[156:159], v[200:203], v[124:127]
	v_mfma_f32_16x16x32_bf16 v[120:123], v[164:167], v[200:203], v[120:123]
	v_mfma_f32_16x16x32_bf16 v[108:111], v[156:159], v[208:211], v[108:111]
	v_mfma_f32_16x16x32_bf16 v[104:107], v[164:167], v[208:211], v[104:107]
	v_mfma_f32_16x16x32_bf16 v[92:95], v[156:159], v[216:219], v[92:95]
	v_mfma_f32_16x16x32_bf16 v[88:91], v[164:167], v[216:219], v[88:91]
	v_mfma_f32_16x16x32_bf16 v[76:79], v[156:159], v[224:227], v[76:79]
	v_mfma_f32_16x16x32_bf16 v[72:75], v[164:167], v[224:227], v[72:75]
	v_mfma_f32_16x16x32_bf16 v[116:119], v[176:179], v[196:199], v[116:119]
	v_mfma_f32_16x16x32_bf16 v[112:115], v[188:191], v[196:199], v[112:115]
	v_mfma_f32_16x16x32_bf16 v[100:103], v[176:179], v[204:207], v[100:103]
	v_mfma_f32_16x16x32_bf16 v[96:99], v[188:191], v[204:207], v[96:99]
	v_mfma_f32_16x16x32_bf16 v[84:87], v[176:179], v[212:215], v[84:87]
	v_mfma_f32_16x16x32_bf16 v[80:83], v[188:191], v[212:215], v[80:83]
	v_mfma_f32_16x16x32_bf16 v[68:71], v[176:179], v[220:223], v[68:71]
	v_mfma_f32_16x16x32_bf16 v[64:67], v[188:191], v[220:223], v[64:67]
	v_mfma_f32_16x16x32_bf16 v[116:119], v[180:183], v[200:203], v[116:119]
	v_mfma_f32_16x16x32_bf16 v[112:115], v[192:195], v[200:203], v[112:115]
	v_mfma_f32_16x16x32_bf16 v[100:103], v[180:183], v[208:211], v[100:103]
	v_mfma_f32_16x16x32_bf16 v[96:99], v[192:195], v[208:211], v[96:99]
	v_mfma_f32_16x16x32_bf16 v[84:87], v[180:183], v[216:219], v[84:87]
	v_mfma_f32_16x16x32_bf16 v[80:83], v[192:195], v[216:219], v[80:83]
	v_mfma_f32_16x16x32_bf16 v[68:71], v[180:183], v[224:227], v[68:71]
	v_mfma_f32_16x16x32_bf16 v[64:67], v[192:195], v[224:227], v[64:67]
	s_setprio 0
	s_barrier
	s_add_i32 s0, s83, s58
	s_mov_b32 m0, s0
	ds_read_b128 v[196:199], v171 offset:49152
	ds_read_b128 v[200:203], v171 offset:50176
	ds_read_b128 v[204:207], v171 offset:51200
	ds_read_b128 v[208:211], v171 offset:52224
	ds_read_b128 v[212:215], v171 offset:53248
	ds_read_b128 v[216:219], v171 offset:54272
	ds_read_b128 v[220:223], v171 offset:55296
	ds_read_b128 v[224:227], v171 offset:56320
	global_load_lds_dwordx4 v136, s[98:99]
	s_add_i32 m0, s0, 0x2000
	s_add_u32 s0, s6, 0x80080
	s_addc_u32 s1, s7, 0
	s_add_i32 s6, s88, s58
	global_load_lds_dwordx4 v140, s[98:99]
	s_mov_b32 m0, s6
	s_nop 0
	global_load_lds_dwordx4 v136, s[0:1]
	s_add_i32 m0, s6, 0x2000
	s_nop 0
	global_load_lds_dwordx4 v140, s[0:1]
	s_mov_b32 m0, s78
	s_nop 0
	global_load_lds_dwordx4 v134, s[100:101]
	s_mov_b32 m0, s79
	s_nop 0
	global_load_lds_dwordx4 v138, s[100:101]
	s_waitcnt vmcnt(8)
	s_waitcnt lgkmcnt(0)
	s_barrier
	s_setprio 1
	s_waitcnt lgkmcnt(0)
	v_mfma_f32_16x16x32_bf16 v[60:63], v[128:131], v[196:199], v[60:63]
	v_mfma_f32_16x16x32_bf16 v[56:59], v[160:163], v[196:199], v[56:59]
	v_mfma_f32_16x16x32_bf16 v[44:47], v[128:131], v[204:207], v[44:47]
	v_mfma_f32_16x16x32_bf16 v[40:43], v[160:163], v[204:207], v[40:43]
	v_mfma_f32_16x16x32_bf16 v[28:31], v[128:131], v[212:215], v[28:31]
	v_mfma_f32_16x16x32_bf16 v[24:27], v[160:163], v[212:215], v[24:27]
	v_mfma_f32_16x16x32_bf16 v[12:15], v[128:131], v[220:223], v[12:15]
	v_mfma_f32_16x16x32_bf16 v[8:11], v[160:163], v[220:223], v[8:11]
	v_mfma_f32_16x16x32_bf16 v[60:63], v[156:159], v[200:203], v[60:63]
	v_mfma_f32_16x16x32_bf16 v[56:59], v[164:167], v[200:203], v[56:59]
	v_mfma_f32_16x16x32_bf16 v[44:47], v[156:159], v[208:211], v[44:47]
	v_mfma_f32_16x16x32_bf16 v[40:43], v[164:167], v[208:211], v[40:43]
	v_mfma_f32_16x16x32_bf16 v[28:31], v[156:159], v[216:219], v[28:31]
	v_mfma_f32_16x16x32_bf16 v[24:27], v[164:167], v[216:219], v[24:27]
	v_mfma_f32_16x16x32_bf16 v[12:15], v[156:159], v[224:227], v[12:15]
	v_mfma_f32_16x16x32_bf16 v[8:11], v[164:167], v[224:227], v[8:11]
	v_mfma_f32_16x16x32_bf16 v[52:55], v[176:179], v[196:199], v[52:55]
	v_mfma_f32_16x16x32_bf16 v[48:51], v[188:191], v[196:199], v[48:51]
	v_mfma_f32_16x16x32_bf16 v[36:39], v[176:179], v[204:207], v[36:39]
	v_mfma_f32_16x16x32_bf16 v[32:35], v[188:191], v[204:207], v[32:35]
	v_mfma_f32_16x16x32_bf16 v[20:23], v[176:179], v[212:215], v[20:23]
	v_mfma_f32_16x16x32_bf16 v[16:19], v[188:191], v[212:215], v[16:19]
	v_mfma_f32_16x16x32_bf16 v[4:7], v[176:179], v[220:223], v[4:7]
	v_mfma_f32_16x16x32_bf16 v[0:3], v[188:191], v[220:223], v[0:3]
	v_mfma_f32_16x16x32_bf16 v[52:55], v[180:183], v[200:203], v[52:55]
	v_mfma_f32_16x16x32_bf16 v[48:51], v[192:195], v[200:203], v[48:51]
	v_mfma_f32_16x16x32_bf16 v[36:39], v[180:183], v[208:211], v[36:39]
	v_mfma_f32_16x16x32_bf16 v[32:35], v[192:195], v[208:211], v[32:35]
	v_mfma_f32_16x16x32_bf16 v[20:23], v[180:183], v[216:219], v[20:23]
	v_mfma_f32_16x16x32_bf16 v[16:19], v[192:195], v[216:219], v[16:19]
	v_mfma_f32_16x16x32_bf16 v[4:7], v[180:183], v[224:227], v[4:7]
	v_mfma_f32_16x16x32_bf16 v[0:3], v[192:195], v[224:227], v[0:3]
	s_setprio 0
	s_barrier
	s_add_i32 vcc_hi, vcc_hi, 2
	s_add_u32 s4, s4, 0x100
	s_addc_u32 s5, s5, 0
	s_add_u32 s57, s57, 0x100
	s_addc_u32 vcc_lo, vcc_lo, 0
	s_cmp_gt_u32 vcc_hi, 29
	s_cbranch_scc0 .LBB0_244
	s_and_b64 vcc, exec, s[28:29]
	s_cbranch_vccz .LBB0_247
	s_barrier

; #define MFMA32(a, b, c) __builtin_amdgcn_mfma_f32_32x32x16_bf16((a), (b), (c), 0, 0, 0)
; __device__ __forceinline__ void hs_slow(int n, int nlast, int tq, int hh, f32x16& S, f32x16 (&O)[4], bf16x8 (&pf)[2], float& lsum, const bf16x8 (&qf)[4], const ATT_LAS unsigned char* ka, const ATT_LAS unsigned char* va) {
;     ...
;     if (n + 1 <= nlast) {
; #pragma unroll
;         for (int s = 0; s < 4; ++s) N = MFMA32(LDF(ka + s * 32), qf[s], N);
;     }
.LBB0_548:
	s_cmp_ge_u32 s45, s42
	s_cbranch_scc1 .LBB0_550
	s_lshr_b32 s4, s43, 1
	s_mul_hi_u32 s46, s4, 0x55555556
	s_mul_i32 s46, s46, 3
	s_sub_i32 s4, s4, s46
	s_add_i32 s46, s25, 0x60
	s_and_b32 s46, s46, 32
	s_mul_i32 s4, s4, 0x8c00
	s_mulk_i32 s46, 0x110
	s_add_i32 s46, s46, s4
	v_add_u32_e32 v1, s46, v163
	ds_read_b128 v[2:5], v1
	ds_read_b128 v[6:9], v1 offset:32
	ds_read_b128 v[10:13], v1 offset:64
	ds_read_b128 v[218:221], v1 offset:96
	s_waitcnt lgkmcnt(3)
	v_mfma_f32_32x32x16_bf16 v[96:111], v[2:5], v[112:115], 0
	s_waitcnt lgkmcnt(2)
	v_mfma_f32_32x32x16_bf16 v[96:111], v[6:9], v[116:119], v[96:111]
	s_waitcnt lgkmcnt(1)
	v_mfma_f32_32x32x16_bf16 v[96:111], v[10:13], v[120:123], v[96:111]
	s_waitcnt lgkmcnt(0)
	v_mfma_f32_32x32x16_bf16 v[96:111], v[218:221], v[124:127], v[96:111]
	s_add_i32 s4, s45, -1
	s_cmp_gt_u32 s4, s42
	s_cbranch_scc0 .LBB0_551
	s_branch .LBB0_552

; #define MFMA32(a, b, c) __builtin_amdgcn_mfma_f32_32x32x16_bf16((a), (b), (c), 0, 0, 0)
; __device__ __forceinline__ void hs_slow(int n, int nlast, int tq, int hh, f32x16& S, f32x16 (&O)[4], bf16x8 (&pf)[2], float& lsum, const bf16x8 (&qf)[4], const ATT_LAS unsigned char* ka, const ATT_LAS unsigned char* va) {
;     ...
;     if (n - 1 >= 1 && n - 1 <= nlast) {
; #pragma unroll
;         for (int s2 = 0; s2 < 2; ++s2)
; #pragma unroll
;             for (int e = 0; e < 4; ++e) O[e] = MFMA32(LDF(va + e * 32 * VPITCH + s2 * 32), pf[s2], O[e]);
;     }
.LBB0_551:
	s_add_i32 s46, s43, 4
	s_lshr_b32 s46, s46, 1
	s_mul_hi_u32 s47, s46, 0x55555556
	s_mul_i32 s47, s47, 3
	s_sub_i32 s46, s46, s47
	s_mul_i32 s46, s46, 0x8c00
	s_and_b32 s47, s44, 64
	s_or_b32 s46, s47, s46
	v_add_u32_e32 v1, s46, v196
	ds_read_b128 v[2:5], v1 offset:17408
	ds_read_b128 v[226:229], v1 offset:22016
	ds_read_b128 v[230:233], v1 offset:26624
	ds_read_b128 v[234:237], v1 offset:31232
	ds_read_b128 v[6:9], v1 offset:17440
	ds_read_b128 v[10:13], v1 offset:22048
	ds_read_b128 v[218:221], v1 offset:26656
	ds_read_b128 v[222:225], v1 offset:31264
	s_waitcnt lgkmcnt(7)
	v_mfma_f32_32x32x16_bf16 v[64:79], v[2:5], v[144:147], v[64:79]
	s_waitcnt lgkmcnt(6)
	v_mfma_f32_32x32x16_bf16 v[48:63], v[226:229], v[144:147], v[48:63]
	s_waitcnt lgkmcnt(5)
	v_mfma_f32_32x32x16_bf16 v[32:47], v[230:233], v[144:147], v[32:47]
	s_waitcnt lgkmcnt(4)
	v_mfma_f32_32x32x16_bf16 v[16:31], v[234:237], v[144:147], v[16:31]
	s_waitcnt lgkmcnt(3)
	v_mfma_f32_32x32x16_bf16 v[64:79], v[6:9], v[148:151], v[64:79]
	s_waitcnt lgkmcnt(2)
	v_mfma_f32_32x32x16_bf16 v[48:63], v[10:13], v[148:151], v[48:63]
	s_waitcnt lgkmcnt(1)
	v_mfma_f32_32x32x16_bf16 v[32:47], v[218:221], v[148:151], v[32:47]
	s_waitcnt lgkmcnt(0)
	v_mfma_f32_32x32x16_bf16 v[16:31], v[222:225], v[148:151], v[16:31]

; #define PG8_STAGE(bufoff, gbase, voff) do { _Pragma("unroll") for (int _i = 0; _i < 2; ++_i) \
;         __builtin_amdgcn_global_load_lds((const unsigned*)((const char*)(gbase) + (voff)[_i]), (PG8_LAS unsigned*)(lds + (bufoff) + ldsw + _i * 8192), 16, 0, 0); } while (0)
; #define PG8_LDA(dst, b, h) do { _Pragma("unroll") for (int m = 0; m < 4; ++m) _Pragma("unroll") for (int k = 0; k < 2; ++k) dst[m][k] = *(const PG8_LAS bf16x8*)(lds + PG8_SA(b, h) + aoff + m * 2048 + k * 1024); } while (0)
; #define PG8_LDB(dst, b, h) do { _Pragma("unroll") for (int n = 0; n < 2; ++n) _Pragma("unroll") for (int k = 0; k < 2; ++k) dst[n][k] = *(const PG8_LAS bf16x8*)(lds + PG8_SB(b, h) + boff + n * 2048 + k * 1024); } while (0)
; #define PG8_MMA(ai, bj, At, Bt) do { __builtin_amdgcn_s_setprio(1); _Pragma("unroll") for (int m = 0; m < 4; ++m) _Pragma("unroll") for (int n = 0; n < 2; ++n) _Pragma("unroll") for (int k = 0; k < 2; ++k) \
;         acc[ai][bj][m][n] = __builtin_amdgcn_mfma_f32_16x16x32_bf16(Bt[n][k], At[m][k], acc[ai][bj][m][n], 0, 0, 0); __builtin_amdgcn_s_setprio(0); } while (0)
; #define PG8_WAIT_V(n) asm volatile("s_waitcnt vmcnt(" #n ")" ::: "memory")
; #define PG8_WAIT_L(n) asm volatile("s_waitcnt lgkmcnt(" #n ")" ::: "memory")
; template <class Epi, class Sched, bool ALIGN_EPI = false, bool SP2 = false>
; __device__ __forceinline__ void gemm_phase(PG8_LAS unsigned char* lds, const Gemm g, const Sched& S, const Epi& E) {
;     ...
;             const bool last = (t == nt - 2);
;             const char* a1 = cA + (size_t)(t + 1) * kstep;
;             const char* a2 = last ? nA : cA + (size_t)(t + 2) * kstep; const char* b2 = last ? nB : cB + (size_t)(t + 2) * kstep;
;             const char* a3 = a2 + kstep; const char* b3 = b2 + kstep;
;             if (last && has_next) S.a_ready(nxt);
;             if constexpr (SP2) {
;             PG8_LDB(B0, 0, 0); PG8_LDB(B1, 0, 1); PG8_SCHED; PG8_LDA(At, 0, 0); PG8_STAGE(PG8_SA(1, 1), a1 + hstep, voffA);
;             PG8_WAIT_V(8); PG8_WAIT_L(0); PG8_BAR; PG8_MMA(0, 0, At, B0); PG8_MMA(0, 1, At, B1); PG8_BAR; PG8_SCHED;
;             PG8_LDA(At, 0, 1); PG8_STAGE(PG8_SB(0, 0), b2, voffB); PG8_STAGE(PG8_SB(0, 1), b2 + hstep, voffB); PG8_STAGE(PG8_SA(0, 0), a2, voffA);
;             PG8_WAIT_V(8); PG8_WAIT_L(0); PG8_BAR; PG8_MMA(1, 0, At, B0); PG8_MMA(1, 1, At, B1); PG8_BAR; PG8_SCHED;
.LBB0_637:
	ds_read_b128 v[144:147], v153
	ds_read_b128 v[158:161], v153 offset:1024
	ds_read_b128 v[162:165], v153 offset:2048
	ds_read_b128 v[166:169], v153 offset:3072
	ds_read_b128 v[170:173], v154
	ds_read_b128 v[174:177], v154 offset:1024
	ds_read_b128 v[178:181], v154 offset:2048
	ds_read_b128 v[182:185], v154 offset:3072
	s_add_u32 s30, s28, 0xfff80080
	s_addc_u32 s31, s29, -1
	s_cmp_eq_u32 s50, 28
	s_cselect_b32 s35, s7, s31
	s_cselect_b32 s34, s21, s30
	s_cselect_b32 s31, s19, s49
	s_cselect_b32 s30, s47, s48
	s_add_i32 m0, s1, 0xc000
	ds_read_b128 v[188:191], v155
	ds_read_b128 v[192:195], v155 offset:1024
	ds_read_b128 v[196:199], v155 offset:2048
	ds_read_b128 v[200:203], v155 offset:3072
	ds_read_b128 v[204:207], v155 offset:4096
	ds_read_b128 v[208:211], v155 offset:5120
	ds_read_b128 v[212:215], v155 offset:6144
	ds_read_b128 v[216:219], v155 offset:7168
	global_load_lds_dwordx4 v136, s[28:29]
	s_add_i32 m0, s1, 0xe000
	s_nop 0
	global_load_lds_dwordx4 v138, s[28:29]
	s_waitcnt vmcnt(8)
	s_waitcnt lgkmcnt(0)
	s_barrier
	s_setprio 1
	s_waitcnt lgkmcnt(0)
	v_mfma_f32_16x16x32_bf16 v[124:127], v[144:147], v[188:191], v[124:127]
	v_mfma_f32_16x16x32_bf16 v[120:123], v[162:165], v[188:191], v[120:123]
	v_mfma_f32_16x16x32_bf16 v[108:111], v[144:147], v[196:199], v[108:111]
	v_mfma_f32_16x16x32_bf16 v[104:107], v[162:165], v[196:199], v[104:107]
	v_mfma_f32_16x16x32_bf16 v[92:95], v[144:147], v[204:207], v[92:95]
	v_mfma_f32_16x16x32_bf16 v[88:91], v[162:165], v[204:207], v[88:91]
	v_mfma_f32_16x16x32_bf16 v[76:79], v[144:147], v[212:215], v[76:79]
	v_mfma_f32_16x16x32_bf16 v[72:75], v[162:165], v[212:215], v[72:75]
	v_mfma_f32_16x16x32_bf16 v[124:127], v[158:161], v[192:195], v[124:127]
	v_mfma_f32_16x16x32_bf16 v[120:123], v[166:169], v[192:195], v[120:123]
	v_mfma_f32_16x16x32_bf16 v[108:111], v[158:161], v[200:203], v[108:111]
	v_mfma_f32_16x16x32_bf16 v[104:107], v[166:169], v[200:203], v[104:107]
	v_mfma_f32_16x16x32_bf16 v[92:95], v[158:161], v[208:211], v[92:95]
	v_mfma_f32_16x16x32_bf16 v[88:91], v[166:169], v[208:211], v[88:91]
	v_mfma_f32_16x16x32_bf16 v[76:79], v[158:161], v[216:219], v[76:79]
	v_mfma_f32_16x16x32_bf16 v[72:75], v[166:169], v[216:219], v[72:75]
	v_mfma_f32_16x16x32_bf16 v[116:119], v[170:173], v[188:191], v[116:119]
	v_mfma_f32_16x16x32_bf16 v[112:115], v[178:181], v[188:191], v[112:115]
	v_mfma_f32_16x16x32_bf16 v[100:103], v[170:173], v[196:199], v[100:103]
	v_mfma_f32_16x16x32_bf16 v[96:99], v[178:181], v[196:199], v[96:99]
	v_mfma_f32_16x16x32_bf16 v[84:87], v[170:173], v[204:207], v[84:87]
	v_mfma_f32_16x16x32_bf16 v[80:83], v[178:181], v[204:207], v[80:83]
	v_mfma_f32_16x16x32_bf16 v[68:71], v[170:173], v[212:215], v[68:71]
	v_mfma_f32_16x16x32_bf16 v[64:67], v[178:181], v[212:215], v[64:67]
	v_mfma_f32_16x16x32_bf16 v[116:119], v[174:177], v[192:195], v[116:119]
	v_mfma_f32_16x16x32_bf16 v[112:115], v[182:185], v[192:195], v[112:115]
	v_mfma_f32_16x16x32_bf16 v[100:103], v[174:177], v[200:203], v[100:103]
	v_mfma_f32_16x16x32_bf16 v[96:99], v[182:185], v[200:203], v[96:99]
	v_mfma_f32_16x16x32_bf16 v[84:87], v[174:177], v[208:211], v[84:87]
	v_mfma_f32_16x16x32_bf16 v[80:83], v[182:185], v[208:211], v[80:83]
	v_mfma_f32_16x16x32_bf16 v[68:71], v[174:177], v[216:219], v[68:71]
	v_mfma_f32_16x16x32_bf16 v[64:67], v[182:185], v[216:219], v[64:67]
	s_setprio 0
	s_barrier
	s_add_u32 s98, s30, s14
	s_addc_u32 s99, s31, s15
	s_add_u32 s100, s34, s14
	s_addc_u32 s101, s35, s15
	s_add_i32 s51, s45, s0
	s_mov_b32 m0, s51
	ds_read_b128 v[188:191], v155 offset:16384
	ds_read_b128 v[192:195], v155 offset:17408
	ds_read_b128 v[196:199], v155 offset:18432
	ds_read_b128 v[200:203], v155 offset:19456
	ds_read_b128 v[204:207], v155 offset:20480
	ds_read_b128 v[208:211], v155 offset:21504
	ds_read_b128 v[212:215], v155 offset:22528
	ds_read_b128 v[216:219], v155 offset:23552
	global_load_lds_dwordx4 v130, s[30:31]
	s_add_i32 m0, s51, 0x2000
	s_add_u32 s54, s30, 0x80000
	s_addc_u32 s55, s31, 0
	s_add_i32 s51, s46, s0
	global_load_lds_dwordx4 v134, s[30:31]
	s_mov_b32 m0, s51
	v_lshl_add_u64 v[224:225], s[34:35], 0, v[132:133]
	global_load_lds_dwordx4 v130, s[54:55]
	s_add_i32 m0, s51, 0x2000
	s_nop 0
	global_load_lds_dwordx4 v134, s[54:55]
	s_mov_b32 m0, s1
	s_nop 0
	global_load_lds_dwordx4 v128, s[34:35]
	s_mov_b32 m0, s27
	s_nop 0
	global_load_lds_dwordx4 v132, s[34:35]
	s_waitcnt vmcnt(8)
	s_waitcnt lgkmcnt(0)
	s_barrier
	s_setprio 1
	s_waitcnt lgkmcnt(0)
	v_mfma_f32_16x16x32_bf16 v[60:63], v[144:147], v[188:191], v[60:63]
	v_mfma_f32_16x16x32_bf16 v[56:59], v[162:165], v[188:191], v[56:59]
	v_mfma_f32_16x16x32_bf16 v[44:47], v[144:147], v[196:199], v[44:47]
	v_mfma_f32_16x16x32_bf16 v[40:43], v[162:165], v[196:199], v[40:43]
	v_mfma_f32_16x16x32_bf16 v[28:31], v[144:147], v[204:207], v[28:31]
	v_mfma_f32_16x16x32_bf16 v[24:27], v[162:165], v[204:207], v[24:27]
	v_mfma_f32_16x16x32_bf16 v[12:15], v[144:147], v[212:215], v[12:15]
	v_mfma_f32_16x16x32_bf16 v[8:11], v[162:165], v[212:215], v[8:11]
	v_mfma_f32_16x16x32_bf16 v[60:63], v[158:161], v[192:195], v[60:63]
	v_mfma_f32_16x16x32_bf16 v[56:59], v[166:169], v[192:195], v[56:59]
	v_mfma_f32_16x16x32_bf16 v[44:47], v[158:161], v[200:203], v[44:47]
	v_mfma_f32_16x16x32_bf16 v[40:43], v[166:169], v[200:203], v[40:43]
	v_mfma_f32_16x16x32_bf16 v[28:31], v[158:161], v[208:211], v[28:31]
	v_mfma_f32_16x16x32_bf16 v[24:27], v[166:169], v[208:211], v[24:27]
	v_mfma_f32_16x16x32_bf16 v[12:15], v[158:161], v[216:219], v[12:15]
	v_mfma_f32_16x16x32_bf16 v[8:11], v[166:169], v[216:219], v[8:11]
	v_mfma_f32_16x16x32_bf16 v[52:55], v[170:173], v[188:191], v[52:55]
	v_mfma_f32_16x16x32_bf16 v[48:51], v[178:181], v[188:191], v[48:51]
	v_mfma_f32_16x16x32_bf16 v[36:39], v[170:173], v[196:199], v[36:39]
	v_mfma_f32_16x16x32_bf16 v[32:35], v[178:181], v[196:199], v[32:35]
	v_mfma_f32_16x16x32_bf16 v[20:23], v[170:173], v[204:207], v[20:23]
	v_mfma_f32_16x16x32_bf16 v[16:19], v[178:181], v[204:207], v[16:19]
	v_mfma_f32_16x16x32_bf16 v[4:7], v[170:173], v[212:215], v[4:7]
	v_mfma_f32_16x16x32_bf16 v[0:3], v[178:181], v[212:215], v[0:3]
	v_mfma_f32_16x16x32_bf16 v[52:55], v[174:177], v[192:195], v[52:55]
	v_mfma_f32_16x16x32_bf16 v[48:51], v[182:185], v[192:195], v[48:51]
	v_mfma_f32_16x16x32_bf16 v[36:39], v[174:177], v[200:203], v[36:39]
	v_mfma_f32_16x16x32_bf16 v[32:35], v[182:185], v[200:203], v[32:35]
	v_mfma_f32_16x16x32_bf16 v[20:23], v[174:177], v[208:211], v[20:23]
	v_mfma_f32_16x16x32_bf16 v[16:19], v[182:185], v[208:211], v[16:19]
	v_mfma_f32_16x16x32_bf16 v[4:7], v[174:177], v[216:219], v[4:7]
	v_mfma_f32_16x16x32_bf16 v[0:3], v[182:185], v[216:219], v[0:3]
	s_setprio 0
	s_barrier
; #define PG8_STAGE(bufoff, gbase, voff) do { _Pragma("unroll") for (int _i = 0; _i < 2; ++_i) \
;         __builtin_amdgcn_global_load_lds((const unsigned*)((const char*)(gbase) + (voff)[_i]), (PG8_LAS unsigned*)(lds + (bufoff) + ldsw + _i * 8192), 16, 0, 0); } while (0)
; #define PG8_LDA(dst, b, h) do { _Pragma("unroll") for (int m = 0; m < 4; ++m) _Pragma("unroll") for (int k = 0; k < 2; ++k) dst[m][k] = *(const PG8_LAS bf16x8*)(lds + PG8_SA(b, h) + aoff + m * 2048 + k * 1024); } while (0)
; #define PG8_LDB(dst, b, h) do { _Pragma("unroll") for (int n = 0; n < 2; ++n) _Pragma("unroll") for (int k = 0; k < 2; ++k) dst[n][k] = *(const PG8_LAS bf16x8*)(lds + PG8_SB(b, h) + boff + n * 2048 + k * 1024); } while (0)
; #define PG8_MMA(ai, bj, At, Bt) do { __builtin_amdgcn_s_setprio(1); _Pragma("unroll") for (int m = 0; m < 4; ++m) _Pragma("unroll") for (int n = 0; n < 2; ++n) _Pragma("unroll") for (int k = 0; k < 2; ++k) \
;         acc[ai][bj][m][n] = __builtin_amdgcn_mfma_f32_16x16x32_bf16(Bt[n][k], At[m][k], acc[ai][bj][m][n], 0, 0, 0); __builtin_amdgcn_s_setprio(0); } while (0)
; #define PG8_WAIT_V(n) asm volatile("s_waitcnt vmcnt(" #n ")" ::: "memory")
; #define PG8_WAIT_L(n) asm volatile("s_waitcnt lgkmcnt(" #n ")" ::: "memory")
; #define PG8_BAR __builtin_amdgcn_s_barrier()
; #define PG8_SCHED __builtin_amdgcn_sched_barrier(0)
; template <class Epi, class Sched, bool ALIGN_EPI = false, bool SP2 = false>
; __device__ __forceinline__ void gemm_phase(PG8_LAS unsigned char* lds, const Gemm g, const Sched& S, const Epi& E) {
;     ...
;             PG8_LDB(B0, 1, 0); PG8_LDB(B1, 1, 1); PG8_SCHED; PG8_LDA(At, 1, 0); PG8_STAGE(PG8_SA(0, 1), a2 + hstep, voffA);
;             PG8_WAIT_V(8); PG8_WAIT_L(0); PG8_BAR; PG8_MMA(0, 0, At, B0); PG8_MMA(0, 1, At, B1); PG8_BAR; PG8_SCHED;
;             PG8_LDA(At, 1, 1); PG8_STAGE(PG8_SB(1, 0), b3, voffB); PG8_STAGE(PG8_SB(1, 1), b3 + hstep, voffB); PG8_STAGE(PG8_SA(1, 0), a3, voffA);
;             PG8_WAIT_V(8); PG8_WAIT_L(0); PG8_BAR; PG8_MMA(1, 0, At, B0); PG8_MMA(1, 1, At, B1); PG8_BAR; PG8_SCHED;
	s_add_i32 s51, 0, 0x18000
	v_add_u32_e32 v157, s51, v152
	s_add_i32 s54, 0, 0x1c000
	ds_read_b128 v[144:147], v157
	ds_read_b128 v[158:161], v157 offset:1024
	ds_read_b128 v[162:165], v157 offset:2048
	ds_read_b128 v[166:169], v157 offset:3072
	v_add_u32_e32 v157, s54, v152
	ds_read_b128 v[170:173], v157
	ds_read_b128 v[174:177], v157 offset:1024
	ds_read_b128 v[178:181], v157 offset:2048
	ds_read_b128 v[182:185], v157 offset:3072
	s_add_u32 s34, s34, 0x80000
	s_addc_u32 s35, s35, 0
	s_mov_b32 m0, s36
	ds_read_b128 v[188:191], v155 offset:32768
	ds_read_b128 v[192:195], v155 offset:33792
	ds_read_b128 v[196:199], v155 offset:34816
	ds_read_b128 v[200:203], v155 offset:35840
	ds_read_b128 v[204:207], v155 offset:36864
	ds_read_b128 v[208:211], v155 offset:37888
	ds_read_b128 v[212:215], v155 offset:38912
	ds_read_b128 v[216:219], v155 offset:39936
	global_load_lds_dwordx4 v128, s[34:35]
	s_mov_b32 m0, s37
	s_nop 0
	global_load_lds_dwordx4 v132, s[34:35]
	s_waitcnt vmcnt(8)
	s_waitcnt lgkmcnt(0)
	s_barrier
	s_setprio 1
	s_waitcnt lgkmcnt(0)
	v_mfma_f32_16x16x32_bf16 v[124:127], v[144:147], v[188:191], v[124:127]
	v_mfma_f32_16x16x32_bf16 v[120:123], v[162:165], v[188:191], v[120:123]
	v_mfma_f32_16x16x32_bf16 v[108:111], v[144:147], v[196:199], v[108:111]
	v_mfma_f32_16x16x32_bf16 v[104:107], v[162:165], v[196:199], v[104:107]
	v_mfma_f32_16x16x32_bf16 v[92:95], v[144:147], v[204:207], v[92:95]
	v_mfma_f32_16x16x32_bf16 v[88:91], v[162:165], v[204:207], v[88:91]
	v_mfma_f32_16x16x32_bf16 v[76:79], v[144:147], v[212:215], v[76:79]
	v_mfma_f32_16x16x32_bf16 v[72:75], v[162:165], v[212:215], v[72:75]
	v_mfma_f32_16x16x32_bf16 v[124:127], v[158:161], v[192:195], v[124:127]
	v_mfma_f32_16x16x32_bf16 v[120:123], v[166:169], v[192:195], v[120:123]
	v_mfma_f32_16x16x32_bf16 v[108:111], v[158:161], v[200:203], v[108:111]
	v_mfma_f32_16x16x32_bf16 v[104:107], v[166:169], v[200:203], v[104:107]
	v_mfma_f32_16x16x32_bf16 v[92:95], v[158:161], v[208:211], v[92:95]
	v_mfma_f32_16x16x32_bf16 v[88:91], v[166:169], v[208:211], v[88:91]
	v_mfma_f32_16x16x32_bf16 v[76:79], v[158:161], v[216:219], v[76:79]
	v_mfma_f32_16x16x32_bf16 v[72:75], v[166:169], v[216:219], v[72:75]
	v_mfma_f32_16x16x32_bf16 v[116:119], v[170:173], v[188:191], v[116:119]
	v_mfma_f32_16x16x32_bf16 v[112:115], v[178:181], v[188:191], v[112:115]
	v_mfma_f32_16x16x32_bf16 v[100:103], v[170:173], v[196:199], v[100:103]
	v_mfma_f32_16x16x32_bf16 v[96:99], v[178:181], v[196:199], v[96:99]
	v_mfma_f32_16x16x32_bf16 v[84:87], v[170:173], v[204:207], v[84:87]
	v_mfma_f32_16x16x32_bf16 v[80:83], v[178:181], v[204:207], v[80:83]
	v_mfma_f32_16x16x32_bf16 v[68:71], v[170:173], v[212:215], v[68:71]
	v_mfma_f32_16x16x32_bf16 v[64:67], v[178:181], v[212:215], v[64:67]
	v_mfma_f32_16x16x32_bf16 v[116:119], v[174:177], v[192:195], v[116:119]
	v_mfma_f32_16x16x32_bf16 v[112:115], v[182:185], v[192:195], v[112:115]
	v_mfma_f32_16x16x32_bf16 v[100:103], v[174:177], v[200:203], v[100:103]
	v_mfma_f32_16x16x32_bf16 v[96:99], v[182:185], v[200:203], v[96:99]
	v_mfma_f32_16x16x32_bf16 v[84:87], v[174:177], v[208:211], v[84:87]
	v_mfma_f32_16x16x32_bf16 v[80:83], v[182:185], v[208:211], v[80:83]
	v_mfma_f32_16x16x32_bf16 v[68:71], v[174:177], v[216:219], v[68:71]
	v_mfma_f32_16x16x32_bf16 v[64:67], v[182:185], v[216:219], v[64:67]
	s_setprio 0
	s_barrier
	s_add_i32 s34, s51, s0
	s_mov_b32 m0, s34
	ds_read_b128 v[188:191], v155 offset:49152
	ds_read_b128 v[192:195], v155 offset:50176
	ds_read_b128 v[196:199], v155 offset:51200
	ds_read_b128 v[200:203], v155 offset:52224
	ds_read_b128 v[204:207], v155 offset:53248
	ds_read_b128 v[208:211], v155 offset:54272
	ds_read_b128 v[212:215], v155 offset:55296
	ds_read_b128 v[216:219], v155 offset:56320
	global_load_lds_dwordx4 v130, s[98:99]
	s_add_i32 m0, s34, 0x2000
	s_add_u32 s30, s30, 0x80080
	s_addc_u32 s31, s31, 0
	s_add_i32 s34, s54, s0
	global_load_lds_dwordx4 v134, s[98:99]
	s_mov_b32 m0, s34
	s_nop 0
	global_load_lds_dwordx4 v130, s[30:31]
	s_add_i32 m0, s34, 0x2000
	s_nop 0
	global_load_lds_dwordx4 v134, s[30:31]
	s_mov_b32 m0, s41
	s_nop 0
	global_load_lds_dwordx4 v128, s[100:101]
	v_lshl_add_u64 v[148:149], v[224:225], 0, s[14:15]
	s_mov_b32 m0, s42
	s_nop 0
	global_load_lds_dwordx4 v132, s[100:101]
	s_waitcnt vmcnt(8)
	s_waitcnt lgkmcnt(0)
	s_barrier
	s_setprio 1
	s_waitcnt lgkmcnt(0)
	v_mfma_f32_16x16x32_bf16 v[60:63], v[144:147], v[188:191], v[60:63]
	v_mfma_f32_16x16x32_bf16 v[56:59], v[162:165], v[188:191], v[56:59]
	v_mfma_f32_16x16x32_bf16 v[44:47], v[144:147], v[196:199], v[44:47]
	v_mfma_f32_16x16x32_bf16 v[40:43], v[162:165], v[196:199], v[40:43]
	v_mfma_f32_16x16x32_bf16 v[28:31], v[144:147], v[204:207], v[28:31]
	v_mfma_f32_16x16x32_bf16 v[24:27], v[162:165], v[204:207], v[24:27]
	v_mfma_f32_16x16x32_bf16 v[12:15], v[144:147], v[212:215], v[12:15]
	v_mfma_f32_16x16x32_bf16 v[8:11], v[162:165], v[212:215], v[8:11]
	v_mfma_f32_16x16x32_bf16 v[60:63], v[158:161], v[192:195], v[60:63]
	v_mfma_f32_16x16x32_bf16 v[56:59], v[166:169], v[192:195], v[56:59]
	v_mfma_f32_16x16x32_bf16 v[44:47], v[158:161], v[200:203], v[44:47]
	v_mfma_f32_16x16x32_bf16 v[40:43], v[166:169], v[200:203], v[40:43]
	v_mfma_f32_16x16x32_bf16 v[28:31], v[158:161], v[208:211], v[28:31]
	v_mfma_f32_16x16x32_bf16 v[24:27], v[166:169], v[208:211], v[24:27]
	v_mfma_f32_16x16x32_bf16 v[12:15], v[158:161], v[216:219], v[12:15]
	v_mfma_f32_16x16x32_bf16 v[8:11], v[166:169], v[216:219], v[8:11]
	v_mfma_f32_16x16x32_bf16 v[52:55], v[170:173], v[188:191], v[52:55]
	v_mfma_f32_16x16x32_bf16 v[48:51], v[178:181], v[188:191], v[48:51]
	v_mfma_f32_16x16x32_bf16 v[36:39], v[170:173], v[196:199], v[36:39]
	v_mfma_f32_16x16x32_bf16 v[32:35], v[178:181], v[196:199], v[32:35]
	v_mfma_f32_16x16x32_bf16 v[20:23], v[170:173], v[204:207], v[20:23]
	v_mfma_f32_16x16x32_bf16 v[16:19], v[178:181], v[204:207], v[16:19]
	v_mfma_f32_16x16x32_bf16 v[4:7], v[170:173], v[212:215], v[4:7]
	v_mfma_f32_16x16x32_bf16 v[0:3], v[178:181], v[212:215], v[0:3]
	v_mfma_f32_16x16x32_bf16 v[52:55], v[174:177], v[192:195], v[52:55]
	v_mfma_f32_16x16x32_bf16 v[48:51], v[182:185], v[192:195], v[48:51]
	v_mfma_f32_16x16x32_bf16 v[36:39], v[174:177], v[200:203], v[36:39]
	v_mfma_f32_16x16x32_bf16 v[32:35], v[182:185], v[200:203], v[32:35]
	v_mfma_f32_16x16x32_bf16 v[20:23], v[174:177], v[208:211], v[20:23]
	v_mfma_f32_16x16x32_bf16 v[16:19], v[182:185], v[208:211], v[16:19]
	v_mfma_f32_16x16x32_bf16 v[4:7], v[174:177], v[216:219], v[4:7]
	v_mfma_f32_16x16x32_bf16 v[0:3], v[182:185], v[216:219], v[0:3]
	s_setprio 0
	s_barrier
	s_add_i32 s50, s50, 2
	s_add_u32 s28, s28, 0x100
	s_addc_u32 s29, s29, 0
	s_add_u32 s48, s48, 0x100
	s_addc_u32 s49, s49, 0
	s_cmp_gt_u32 s50, 29
	s_cbranch_scc0 .LBB0_637
	s_and_b64 vcc, exec, s[16:17]
	s_cbranch_vccz .LBB0_640
	s_barrier

; #define PG8_STAGE(bufoff, gbase, voff) do { _Pragma("unroll") for (int _i = 0; _i < 2; ++_i) \
;         __builtin_amdgcn_global_load_lds((const unsigned*)((const char*)(gbase) + (voff)[_i]), (PG8_LAS unsigned*)(lds + (bufoff) + ldsw + _i * 8192), 16, 0, 0); } while (0)
; #define PG8_LDA(dst, b, h) do { _Pragma("unroll") for (int m = 0; m < 4; ++m) _Pragma("unroll") for (int k = 0; k < 2; ++k) dst[m][k] = *(const PG8_LAS bf16x8*)(lds + PG8_SA(b, h) + aoff + m * 2048 + k * 1024); } while (0)
; #define PG8_LDB(dst, b, h) do { _Pragma("unroll") for (int n = 0; n < 2; ++n) _Pragma("unroll") for (int k = 0; k < 2; ++k) dst[n][k] = *(const PG8_LAS bf16x8*)(lds + PG8_SB(b, h) + boff + n * 2048 + k * 1024); } while (0)
; #define PG8_MMA(ai, bj, At, Bt) do { __builtin_amdgcn_s_setprio(1); _Pragma("unroll") for (int m = 0; m < 4; ++m) _Pragma("unroll") for (int n = 0; n < 2; ++n) _Pragma("unroll") for (int k = 0; k < 2; ++k) \
;         acc[ai][bj][m][n] = __builtin_amdgcn_mfma_f32_16x16x32_bf16(Bt[n][k], At[m][k], acc[ai][bj][m][n], 0, 0, 0); __builtin_amdgcn_s_setprio(0); } while (0)
; #define PG8_WAIT_V(n) asm volatile("s_waitcnt vmcnt(" #n ")" ::: "memory")
; #define PG8_WAIT_L(n) asm volatile("s_waitcnt lgkmcnt(" #n ")" ::: "memory")
; #define PG8_BAR __builtin_amdgcn_s_barrier()
; template <class Epi, class Sched, bool ALIGN_EPI = false, bool SP2 = false>
; __device__ __forceinline__ void gemm_phase(PG8_LAS unsigned char* lds, const Gemm g, const Sched& S, const Epi& E) {
;     ...
;             const char* a1 = cA + (size_t)(t + 1) * kstep;
;             const char* a2 = last ? nA : cA + (size_t)(t + 2) * kstep; const char* b2 = last ? nB : cB + (size_t)(t + 2) * kstep;
;             const char* a3 = a2 + kstep; const char* b3 = b2 + kstep;
;             if (last && has_next) S.a_ready(nxt);
;             if constexpr (SP2) {
;             PG8_LDB(B0, 0, 0); PG8_LDB(B1, 0, 1); PG8_SCHED; PG8_LDA(At, 0, 0); PG8_STAGE(PG8_SA(1, 1), a1 + hstep, voffA);
;             PG8_WAIT_V(8); PG8_WAIT_L(0); PG8_BAR; PG8_MMA(0, 0, At, B0); PG8_MMA(0, 1, At, B1); PG8_BAR; PG8_SCHED;
;             PG8_LDA(At, 0, 1); PG8_STAGE(PG8_SB(0, 0), b2, voffB); PG8_STAGE(PG8_SB(0, 1), b2 + hstep, voffB); PG8_STAGE(PG8_SA(0, 0), a2, voffA);
;             PG8_WAIT_V(8); PG8_WAIT_L(0); PG8_BAR; PG8_MMA(1, 0, At, B0); PG8_MMA(1, 1, At, B1); PG8_BAR; PG8_SCHED;
.LBB0_728:
	ds_read_b128 v[144:147], v151
	ds_read_b128 v[156:159], v151 offset:1024
	ds_read_b128 v[160:163], v151 offset:2048
	ds_read_b128 v[164:167], v151 offset:3072
	ds_read_b128 v[168:171], v152
	ds_read_b128 v[172:175], v152 offset:1024
	ds_read_b128 v[176:179], v152 offset:2048
	ds_read_b128 v[180:183], v152 offset:3072
	s_add_u32 s28, s26, 0xfff80080
	s_addc_u32 s29, s27, -1
	s_cmp_eq_u32 s51, 28
	s_cselect_b32 s31, s19, s29
	s_cselect_b32 s30, s47, s28
	s_cselect_b32 s29, s17, s50
	s_cselect_b32 s28, s48, s49
	s_add_i32 m0, s25, 0xc000
	ds_read_b128 v[188:191], v153
	ds_read_b128 v[192:195], v153 offset:1024
	ds_read_b128 v[196:199], v153 offset:2048
	ds_read_b128 v[200:203], v153 offset:3072
	ds_read_b128 v[204:207], v153 offset:4096
	ds_read_b128 v[208:211], v153 offset:5120
	ds_read_b128 v[212:215], v153 offset:6144
	ds_read_b128 v[216:219], v153 offset:7168
	global_load_lds_dwordx4 v136, s[26:27]
	s_add_i32 m0, s25, 0xe000
	s_nop 0
	global_load_lds_dwordx4 v138, s[26:27]
	s_waitcnt vmcnt(8)
	s_waitcnt lgkmcnt(0)
	s_barrier
	s_setprio 1
	s_waitcnt lgkmcnt(0)
	v_mfma_f32_16x16x32_bf16 v[124:127], v[144:147], v[188:191], v[124:127]
	v_mfma_f32_16x16x32_bf16 v[120:123], v[160:163], v[188:191], v[120:123]
	v_mfma_f32_16x16x32_bf16 v[108:111], v[144:147], v[196:199], v[108:111]
	v_mfma_f32_16x16x32_bf16 v[104:107], v[160:163], v[196:199], v[104:107]
	v_mfma_f32_16x16x32_bf16 v[92:95], v[144:147], v[204:207], v[92:95]
	v_mfma_f32_16x16x32_bf16 v[88:91], v[160:163], v[204:207], v[88:91]
	v_mfma_f32_16x16x32_bf16 v[76:79], v[144:147], v[212:215], v[76:79]
	v_mfma_f32_16x16x32_bf16 v[72:75], v[160:163], v[212:215], v[72:75]
	v_mfma_f32_16x16x32_bf16 v[124:127], v[156:159], v[192:195], v[124:127]
	v_mfma_f32_16x16x32_bf16 v[120:123], v[164:167], v[192:195], v[120:123]
	v_mfma_f32_16x16x32_bf16 v[108:111], v[156:159], v[200:203], v[108:111]
	v_mfma_f32_16x16x32_bf16 v[104:107], v[164:167], v[200:203], v[104:107]
	v_mfma_f32_16x16x32_bf16 v[92:95], v[156:159], v[208:211], v[92:95]
	v_mfma_f32_16x16x32_bf16 v[88:91], v[164:167], v[208:211], v[88:91]
	v_mfma_f32_16x16x32_bf16 v[76:79], v[156:159], v[216:219], v[76:79]
	v_mfma_f32_16x16x32_bf16 v[72:75], v[164:167], v[216:219], v[72:75]
	v_mfma_f32_16x16x32_bf16 v[116:119], v[168:171], v[188:191], v[116:119]
	v_mfma_f32_16x16x32_bf16 v[112:115], v[176:179], v[188:191], v[112:115]
	v_mfma_f32_16x16x32_bf16 v[100:103], v[168:171], v[196:199], v[100:103]
	v_mfma_f32_16x16x32_bf16 v[96:99], v[176:179], v[196:199], v[96:99]
	v_mfma_f32_16x16x32_bf16 v[84:87], v[168:171], v[204:207], v[84:87]
	v_mfma_f32_16x16x32_bf16 v[80:83], v[176:179], v[204:207], v[80:83]
	v_mfma_f32_16x16x32_bf16 v[68:71], v[168:171], v[212:215], v[68:71]
	v_mfma_f32_16x16x32_bf16 v[64:67], v[176:179], v[212:215], v[64:67]
	v_mfma_f32_16x16x32_bf16 v[116:119], v[172:175], v[192:195], v[116:119]
	v_mfma_f32_16x16x32_bf16 v[112:115], v[180:183], v[192:195], v[112:115]
	v_mfma_f32_16x16x32_bf16 v[100:103], v[172:175], v[200:203], v[100:103]
	v_mfma_f32_16x16x32_bf16 v[96:99], v[180:183], v[200:203], v[96:99]
	v_mfma_f32_16x16x32_bf16 v[84:87], v[172:175], v[208:211], v[84:87]
	v_mfma_f32_16x16x32_bf16 v[80:83], v[180:183], v[208:211], v[80:83]
	v_mfma_f32_16x16x32_bf16 v[68:71], v[172:175], v[216:219], v[68:71]
	v_mfma_f32_16x16x32_bf16 v[64:67], v[180:183], v[216:219], v[64:67]
	s_setprio 0
	s_barrier
	s_add_u32 s98, s28, s12
	s_addc_u32 s99, s29, s13
	s_add_u32 s100, s30, s12
	s_addc_u32 s101, s31, s13
	s_add_i32 s54, s43, s1
	s_mov_b32 m0, s54
	ds_read_b128 v[188:191], v153 offset:16384
	ds_read_b128 v[192:195], v153 offset:17408
	ds_read_b128 v[196:199], v153 offset:18432
	ds_read_b128 v[200:203], v153 offset:19456
	ds_read_b128 v[204:207], v153 offset:20480
	ds_read_b128 v[208:211], v153 offset:21504
	ds_read_b128 v[212:215], v153 offset:22528
	ds_read_b128 v[216:219], v153 offset:23552
	global_load_lds_dwordx4 v130, s[28:29]
	s_add_i32 m0, s54, 0x2000
	s_add_u32 s54, s28, 0x80000
	s_addc_u32 s55, s29, 0
	s_add_i32 s56, s44, s1
	global_load_lds_dwordx4 v134, s[28:29]
	s_mov_b32 m0, s56
	s_nop 0
	global_load_lds_dwordx4 v130, s[54:55]
	s_add_i32 m0, s56, 0x2000
	s_nop 0
	global_load_lds_dwordx4 v134, s[54:55]
	s_mov_b32 m0, s25
	s_nop 0
	global_load_lds_dwordx4 v128, s[30:31]
	s_mov_b32 m0, s34
	s_nop 0
	global_load_lds_dwordx4 v132, s[30:31]
	s_waitcnt vmcnt(8)
	s_waitcnt lgkmcnt(0)
	s_barrier
	s_setprio 1
	s_waitcnt lgkmcnt(0)
	v_mfma_f32_16x16x32_bf16 v[60:63], v[144:147], v[188:191], v[60:63]
	v_mfma_f32_16x16x32_bf16 v[56:59], v[160:163], v[188:191], v[56:59]
	v_mfma_f32_16x16x32_bf16 v[44:47], v[144:147], v[196:199], v[44:47]
	v_mfma_f32_16x16x32_bf16 v[40:43], v[160:163], v[196:199], v[40:43]
	v_mfma_f32_16x16x32_bf16 v[28:31], v[144:147], v[204:207], v[28:31]
	v_mfma_f32_16x16x32_bf16 v[24:27], v[160:163], v[204:207], v[24:27]
	v_mfma_f32_16x16x32_bf16 v[12:15], v[144:147], v[212:215], v[12:15]
	v_mfma_f32_16x16x32_bf16 v[8:11], v[160:163], v[212:215], v[8:11]
	v_mfma_f32_16x16x32_bf16 v[60:63], v[156:159], v[192:195], v[60:63]
	v_mfma_f32_16x16x32_bf16 v[56:59], v[164:167], v[192:195], v[56:59]
	v_mfma_f32_16x16x32_bf16 v[44:47], v[156:159], v[200:203], v[44:47]
	v_mfma_f32_16x16x32_bf16 v[40:43], v[164:167], v[200:203], v[40:43]
	v_mfma_f32_16x16x32_bf16 v[28:31], v[156:159], v[208:211], v[28:31]
	v_mfma_f32_16x16x32_bf16 v[24:27], v[164:167], v[208:211], v[24:27]
	v_mfma_f32_16x16x32_bf16 v[12:15], v[156:159], v[216:219], v[12:15]
	v_mfma_f32_16x16x32_bf16 v[8:11], v[164:167], v[216:219], v[8:11]
	v_mfma_f32_16x16x32_bf16 v[52:55], v[168:171], v[188:191], v[52:55]
	v_mfma_f32_16x16x32_bf16 v[48:51], v[176:179], v[188:191], v[48:51]
	v_mfma_f32_16x16x32_bf16 v[36:39], v[168:171], v[196:199], v[36:39]
	v_mfma_f32_16x16x32_bf16 v[32:35], v[176:179], v[196:199], v[32:35]
	v_mfma_f32_16x16x32_bf16 v[20:23], v[168:171], v[204:207], v[20:23]
	v_mfma_f32_16x16x32_bf16 v[16:19], v[176:179], v[204:207], v[16:19]
	v_mfma_f32_16x16x32_bf16 v[4:7], v[168:171], v[212:215], v[4:7]
	v_mfma_f32_16x16x32_bf16 v[0:3], v[176:179], v[212:215], v[0:3]
	v_mfma_f32_16x16x32_bf16 v[52:55], v[172:175], v[192:195], v[52:55]
	v_mfma_f32_16x16x32_bf16 v[48:51], v[180:183], v[192:195], v[48:51]
	v_mfma_f32_16x16x32_bf16 v[36:39], v[172:175], v[200:203], v[36:39]
	v_mfma_f32_16x16x32_bf16 v[32:35], v[180:183], v[200:203], v[32:35]
	v_mfma_f32_16x16x32_bf16 v[20:23], v[172:175], v[208:211], v[20:23]
	v_mfma_f32_16x16x32_bf16 v[16:19], v[180:183], v[208:211], v[16:19]
	v_mfma_f32_16x16x32_bf16 v[4:7], v[172:175], v[216:219], v[4:7]
	v_mfma_f32_16x16x32_bf16 v[0:3], v[180:183], v[216:219], v[0:3]
	s_setprio 0
	s_barrier
; #define PG8_STAGE(bufoff, gbase, voff) do { _Pragma("unroll") for (int _i = 0; _i < 2; ++_i) \
;         __builtin_amdgcn_global_load_lds((const unsigned*)((const char*)(gbase) + (voff)[_i]), (PG8_LAS unsigned*)(lds + (bufoff) + ldsw + _i * 8192), 16, 0, 0); } while (0)
; #define PG8_LDA(dst, b, h) do { _Pragma("unroll") for (int m = 0; m < 4; ++m) _Pragma("unroll") for (int k = 0; k < 2; ++k) dst[m][k] = *(const PG8_LAS bf16x8*)(lds + PG8_SA(b, h) + aoff + m * 2048 + k * 1024); } while (0)
; #define PG8_LDB(dst, b, h) do { _Pragma("unroll") for (int n = 0; n < 2; ++n) _Pragma("unroll") for (int k = 0; k < 2; ++k) dst[n][k] = *(const PG8_LAS bf16x8*)(lds + PG8_SB(b, h) + boff + n * 2048 + k * 1024); } while (0)
; #define PG8_MMA(ai, bj, At, Bt) do { __builtin_amdgcn_s_setprio(1); _Pragma("unroll") for (int m = 0; m < 4; ++m) _Pragma("unroll") for (int n = 0; n < 2; ++n) _Pragma("unroll") for (int k = 0; k < 2; ++k) \
;         acc[ai][bj][m][n] = __builtin_amdgcn_mfma_f32_16x16x32_bf16(Bt[n][k], At[m][k], acc[ai][bj][m][n], 0, 0, 0); __builtin_amdgcn_s_setprio(0); } while (0)
; #define PG8_WAIT_V(n) asm volatile("s_waitcnt vmcnt(" #n ")" ::: "memory")
; #define PG8_WAIT_L(n) asm volatile("s_waitcnt lgkmcnt(" #n ")" ::: "memory")
; #define PG8_BAR __builtin_amdgcn_s_barrier()
; #define PG8_SCHED __builtin_amdgcn_sched_barrier(0)
; template <class Epi, class Sched, bool ALIGN_EPI = false, bool SP2 = false>
; __device__ __forceinline__ void gemm_phase(PG8_LAS unsigned char* lds, const Gemm g, const Sched& S, const Epi& E) {
;     ...
;             PG8_LDB(B0, 1, 0); PG8_LDB(B1, 1, 1); PG8_SCHED; PG8_LDA(At, 1, 0); PG8_STAGE(PG8_SA(0, 1), a2 + hstep, voffA);
;             PG8_WAIT_V(8); PG8_WAIT_L(0); PG8_BAR; PG8_MMA(0, 0, At, B0); PG8_MMA(0, 1, At, B1); PG8_BAR; PG8_SCHED;
;             PG8_LDA(At, 1, 1); PG8_STAGE(PG8_SB(1, 0), b3, voffB); PG8_STAGE(PG8_SB(1, 1), b3 + hstep, voffB); PG8_STAGE(PG8_SA(1, 0), a3, voffA);
;             PG8_WAIT_V(8); PG8_WAIT_L(0); PG8_BAR; PG8_MMA(1, 0, At, B0); PG8_MMA(1, 1, At, B1); PG8_BAR; PG8_SCHED;
;     ...
;         if constexpr (ALIGN_EPI) { if (wr == 0) PG8_BAR; }
	s_add_i32 s54, 0, 0x18000
	v_add_u32_e32 v155, s54, v150
	s_add_i32 s55, 0, 0x1c000
	ds_read_b128 v[144:147], v155
	ds_read_b128 v[156:159], v155 offset:1024
	ds_read_b128 v[160:163], v155 offset:2048
	ds_read_b128 v[164:167], v155 offset:3072
	v_add_u32_e32 v155, s55, v150
	ds_read_b128 v[168:171], v155
	ds_read_b128 v[172:175], v155 offset:1024
	ds_read_b128 v[176:179], v155 offset:2048
	ds_read_b128 v[180:183], v155 offset:3072
	s_add_u32 s30, s30, 0x80000
	s_addc_u32 s31, s31, 0
	s_mov_b32 m0, s35
	ds_read_b128 v[188:191], v153 offset:32768
	ds_read_b128 v[192:195], v153 offset:33792
	ds_read_b128 v[196:199], v153 offset:34816
	ds_read_b128 v[200:203], v153 offset:35840
	ds_read_b128 v[204:207], v153 offset:36864
	ds_read_b128 v[208:211], v153 offset:37888
	ds_read_b128 v[212:215], v153 offset:38912
	ds_read_b128 v[216:219], v153 offset:39936
	global_load_lds_dwordx4 v128, s[30:31]
	s_mov_b32 m0, s36
	s_nop 0
	global_load_lds_dwordx4 v132, s[30:31]
	s_waitcnt vmcnt(8)
	s_waitcnt lgkmcnt(0)
	s_barrier
	s_setprio 1
	s_waitcnt lgkmcnt(0)
	v_mfma_f32_16x16x32_bf16 v[124:127], v[144:147], v[188:191], v[124:127]
	v_mfma_f32_16x16x32_bf16 v[120:123], v[160:163], v[188:191], v[120:123]
	v_mfma_f32_16x16x32_bf16 v[108:111], v[144:147], v[196:199], v[108:111]
	v_mfma_f32_16x16x32_bf16 v[104:107], v[160:163], v[196:199], v[104:107]
	v_mfma_f32_16x16x32_bf16 v[92:95], v[144:147], v[204:207], v[92:95]
	v_mfma_f32_16x16x32_bf16 v[88:91], v[160:163], v[204:207], v[88:91]
	v_mfma_f32_16x16x32_bf16 v[76:79], v[144:147], v[212:215], v[76:79]
	v_mfma_f32_16x16x32_bf16 v[72:75], v[160:163], v[212:215], v[72:75]
	v_mfma_f32_16x16x32_bf16 v[124:127], v[156:159], v[192:195], v[124:127]
	v_mfma_f32_16x16x32_bf16 v[120:123], v[164:167], v[192:195], v[120:123]
	v_mfma_f32_16x16x32_bf16 v[108:111], v[156:159], v[200:203], v[108:111]
	v_mfma_f32_16x16x32_bf16 v[104:107], v[164:167], v[200:203], v[104:107]
	v_mfma_f32_16x16x32_bf16 v[92:95], v[156:159], v[208:211], v[92:95]
	v_mfma_f32_16x16x32_bf16 v[88:91], v[164:167], v[208:211], v[88:91]
	v_mfma_f32_16x16x32_bf16 v[76:79], v[156:159], v[216:219], v[76:79]
	v_mfma_f32_16x16x32_bf16 v[72:75], v[164:167], v[216:219], v[72:75]
	v_mfma_f32_16x16x32_bf16 v[116:119], v[168:171], v[188:191], v[116:119]
	v_mfma_f32_16x16x32_bf16 v[112:115], v[176:179], v[188:191], v[112:115]
	v_mfma_f32_16x16x32_bf16 v[100:103], v[168:171], v[196:199], v[100:103]
	v_mfma_f32_16x16x32_bf16 v[96:99], v[176:179], v[196:199], v[96:99]
	v_mfma_f32_16x16x32_bf16 v[84:87], v[168:171], v[204:207], v[84:87]
	v_mfma_f32_16x16x32_bf16 v[80:83], v[176:179], v[204:207], v[80:83]
	v_mfma_f32_16x16x32_bf16 v[68:71], v[168:171], v[212:215], v[68:71]
	v_mfma_f32_16x16x32_bf16 v[64:67], v[176:179], v[212:215], v[64:67]
	v_mfma_f32_16x16x32_bf16 v[116:119], v[172:175], v[192:195], v[116:119]
	v_mfma_f32_16x16x32_bf16 v[112:115], v[180:183], v[192:195], v[112:115]
	v_mfma_f32_16x16x32_bf16 v[100:103], v[172:175], v[200:203], v[100:103]
	v_mfma_f32_16x16x32_bf16 v[96:99], v[180:183], v[200:203], v[96:99]
	v_mfma_f32_16x16x32_bf16 v[84:87], v[172:175], v[208:211], v[84:87]
	v_mfma_f32_16x16x32_bf16 v[80:83], v[180:183], v[208:211], v[80:83]
	v_mfma_f32_16x16x32_bf16 v[68:71], v[172:175], v[216:219], v[68:71]
	v_mfma_f32_16x16x32_bf16 v[64:67], v[180:183], v[216:219], v[64:67]
	s_setprio 0
	s_barrier
	s_add_i32 s30, s54, s1
	s_mov_b32 m0, s30
	ds_read_b128 v[188:191], v153 offset:49152
	ds_read_b128 v[192:195], v153 offset:50176
	ds_read_b128 v[196:199], v153 offset:51200
	ds_read_b128 v[200:203], v153 offset:52224
	ds_read_b128 v[204:207], v153 offset:53248
	ds_read_b128 v[208:211], v153 offset:54272
	ds_read_b128 v[212:215], v153 offset:55296
	ds_read_b128 v[216:219], v153 offset:56320
	global_load_lds_dwordx4 v130, s[98:99]
	s_add_i32 m0, s30, 0x2000
	s_add_u32 s28, s28, 0x80080
	s_addc_u32 s29, s29, 0
	s_add_i32 s30, s55, s1
	global_load_lds_dwordx4 v134, s[98:99]
	s_mov_b32 m0, s30
	s_nop 0
	global_load_lds_dwordx4 v130, s[28:29]
	s_add_i32 m0, s30, 0x2000
	s_nop 0
	global_load_lds_dwordx4 v134, s[28:29]
	s_mov_b32 m0, s40
	s_nop 0
	global_load_lds_dwordx4 v128, s[100:101]
	s_mov_b32 m0, s41
	s_nop 0
	global_load_lds_dwordx4 v132, s[100:101]
	s_waitcnt vmcnt(8)
	s_waitcnt lgkmcnt(0)
	s_barrier
	s_setprio 1
	s_waitcnt lgkmcnt(0)
	v_mfma_f32_16x16x32_bf16 v[60:63], v[144:147], v[188:191], v[60:63]
	v_mfma_f32_16x16x32_bf16 v[56:59], v[160:163], v[188:191], v[56:59]
	v_mfma_f32_16x16x32_bf16 v[44:47], v[144:147], v[196:199], v[44:47]
	v_mfma_f32_16x16x32_bf16 v[40:43], v[160:163], v[196:199], v[40:43]
	v_mfma_f32_16x16x32_bf16 v[28:31], v[144:147], v[204:207], v[28:31]
	v_mfma_f32_16x16x32_bf16 v[24:27], v[160:163], v[204:207], v[24:27]
	v_mfma_f32_16x16x32_bf16 v[12:15], v[144:147], v[212:215], v[12:15]
	v_mfma_f32_16x16x32_bf16 v[8:11], v[160:163], v[212:215], v[8:11]
	v_mfma_f32_16x16x32_bf16 v[60:63], v[156:159], v[192:195], v[60:63]
	v_mfma_f32_16x16x32_bf16 v[56:59], v[164:167], v[192:195], v[56:59]
	v_mfma_f32_16x16x32_bf16 v[44:47], v[156:159], v[200:203], v[44:47]
	v_mfma_f32_16x16x32_bf16 v[40:43], v[164:167], v[200:203], v[40:43]
	v_mfma_f32_16x16x32_bf16 v[28:31], v[156:159], v[208:211], v[28:31]
	v_mfma_f32_16x16x32_bf16 v[24:27], v[164:167], v[208:211], v[24:27]
	v_mfma_f32_16x16x32_bf16 v[12:15], v[156:159], v[216:219], v[12:15]
	v_mfma_f32_16x16x32_bf16 v[8:11], v[164:167], v[216:219], v[8:11]
	v_mfma_f32_16x16x32_bf16 v[52:55], v[168:171], v[188:191], v[52:55]
	v_mfma_f32_16x16x32_bf16 v[48:51], v[176:179], v[188:191], v[48:51]
	v_mfma_f32_16x16x32_bf16 v[36:39], v[168:171], v[196:199], v[36:39]
	v_mfma_f32_16x16x32_bf16 v[32:35], v[176:179], v[196:199], v[32:35]
	v_mfma_f32_16x16x32_bf16 v[20:23], v[168:171], v[204:207], v[20:23]
	v_mfma_f32_16x16x32_bf16 v[16:19], v[176:179], v[204:207], v[16:19]
	v_mfma_f32_16x16x32_bf16 v[4:7], v[168:171], v[212:215], v[4:7]
	v_mfma_f32_16x16x32_bf16 v[0:3], v[176:179], v[212:215], v[0:3]
	v_mfma_f32_16x16x32_bf16 v[52:55], v[172:175], v[192:195], v[52:55]
	v_mfma_f32_16x16x32_bf16 v[48:51], v[180:183], v[192:195], v[48:51]
	v_mfma_f32_16x16x32_bf16 v[36:39], v[172:175], v[200:203], v[36:39]
	v_mfma_f32_16x16x32_bf16 v[32:35], v[180:183], v[200:203], v[32:35]
	v_mfma_f32_16x16x32_bf16 v[20:23], v[172:175], v[208:211], v[20:23]
	v_mfma_f32_16x16x32_bf16 v[16:19], v[180:183], v[208:211], v[16:19]
	v_mfma_f32_16x16x32_bf16 v[4:7], v[172:175], v[216:219], v[4:7]
	v_mfma_f32_16x16x32_bf16 v[0:3], v[180:183], v[216:219], v[0:3]
	s_setprio 0
	s_barrier
	s_add_i32 s51, s51, 2
	s_add_u32 s26, s26, 0x100
	s_addc_u32 s27, s27, 0
	s_add_u32 s49, s49, 0x100
	s_addc_u32 s50, s50, 0
	s_cmp_gt_u32 s51, 29
	s_cbranch_scc0 .LBB0_728
	s_and_b64 vcc, exec, s[14:15]
	s_cbranch_vccz .LBB0_731
	s_barrier

; #define PG8_STAGE(bufoff, gbase, voff) do { _Pragma("unroll") for (int _i = 0; _i < 2; ++_i) \
;         __builtin_amdgcn_global_load_lds((const unsigned*)((const char*)(gbase) + (voff)[_i]), (PG8_LAS unsigned*)(lds + (bufoff) + ldsw + _i * 8192), 16, 0, 0); } while (0)
; #define PG8_LDA(dst, b, h) do { _Pragma("unroll") for (int m = 0; m < 4; ++m) _Pragma("unroll") for (int k = 0; k < 2; ++k) dst[m][k] = *(const PG8_LAS bf16x8*)(lds + PG8_SA(b, h) + aoff + m * 2048 + k * 1024); } while (0)
; #define PG8_LDB(dst, b, h) do { _Pragma("unroll") for (int n = 0; n < 2; ++n) _Pragma("unroll") for (int k = 0; k < 2; ++k) dst[n][k] = *(const PG8_LAS bf16x8*)(lds + PG8_SB(b, h) + boff + n * 2048 + k * 1024); } while (0)
; #define PG8_MMA(ai, bj, At, Bt) do { __builtin_amdgcn_s_setprio(1); _Pragma("unroll") for (int m = 0; m < 4; ++m) _Pragma("unroll") for (int n = 0; n < 2; ++n) _Pragma("unroll") for (int k = 0; k < 2; ++k) \
;         acc[ai][bj][m][n] = __builtin_amdgcn_mfma_f32_16x16x32_bf16(Bt[n][k], At[m][k], acc[ai][bj][m][n], 0, 0, 0); __builtin_amdgcn_s_setprio(0); } while (0)
; #define PG8_WAIT_V(n) asm volatile("s_waitcnt vmcnt(" #n ")" ::: "memory")
; #define PG8_WAIT_L(n) asm volatile("s_waitcnt lgkmcnt(" #n ")" ::: "memory")
; #define PG8_BAR __builtin_amdgcn_s_barrier()
; template <class Epi, class Sched, bool ALIGN_EPI = false, bool SP2 = false>
; __device__ __forceinline__ void gemm_phase(PG8_LAS unsigned char* lds, const Gemm g, const Sched& S, const Epi& E) {
;     ...
;             const char* a1 = cA + (size_t)(t + 1) * kstep;
;             const char* a2 = last ? nA : cA + (size_t)(t + 2) * kstep; const char* b2 = last ? nB : cB + (size_t)(t + 2) * kstep;
;             const char* a3 = a2 + kstep; const char* b3 = b2 + kstep;
;             if (last && has_next) S.a_ready(nxt);
;             if constexpr (SP2) {
;             PG8_LDB(B0, 0, 0); PG8_LDB(B1, 0, 1); PG8_SCHED; PG8_LDA(At, 0, 0); PG8_STAGE(PG8_SA(1, 1), a1 + hstep, voffA);
;             PG8_WAIT_V(8); PG8_WAIT_L(0); PG8_BAR; PG8_MMA(0, 0, At, B0); PG8_MMA(0, 1, At, B1); PG8_BAR; PG8_SCHED;
;             PG8_LDA(At, 0, 1); PG8_STAGE(PG8_SB(0, 0), b2, voffB); PG8_STAGE(PG8_SB(0, 1), b2 + hstep, voffB); PG8_STAGE(PG8_SA(0, 0), a2, voffA);
;             PG8_WAIT_V(8); PG8_WAIT_L(0); PG8_BAR; PG8_MMA(1, 0, At, B0); PG8_MMA(1, 1, At, B1); PG8_BAR; PG8_SCHED;
.LBB0_803:
	ds_read_b128 v[144:147], v151
	ds_read_b128 v[154:157], v151 offset:1024
	ds_read_b128 v[158:161], v151 offset:2048
	ds_read_b128 v[162:165], v151 offset:3072
	ds_read_b128 v[166:169], v152
	ds_read_b128 v[170:173], v152 offset:1024
	ds_read_b128 v[174:177], v152 offset:2048
	ds_read_b128 v[178:181], v152 offset:3072
	s_add_u32 s30, s28, 0xffe00080
	s_addc_u32 s31, s29, -1
	s_cmpk_eq_i32 s51, 0x7c
	s_cselect_b32 s35, s21, s31
	s_cselect_b32 s34, s47, s30
	s_cselect_b32 s31, s19, s50
	s_cselect_b32 s30, s48, s49
	s_add_i32 m0, s27, 0xc000
	ds_read_b128 v[182:185], v153
	ds_read_b128 v[188:191], v153 offset:1024
	ds_read_b128 v[192:195], v153 offset:2048
	ds_read_b128 v[196:199], v153 offset:3072
	ds_read_b128 v[200:203], v153 offset:4096
	ds_read_b128 v[204:207], v153 offset:5120
	ds_read_b128 v[208:211], v153 offset:6144
	ds_read_b128 v[212:215], v153 offset:7168
	global_load_lds_dwordx4 v136, s[28:29]
	s_add_i32 m0, s27, 0xe000
	s_nop 0
	global_load_lds_dwordx4 v138, s[28:29]
	s_waitcnt vmcnt(8)
	s_waitcnt lgkmcnt(0)
	s_barrier
	s_setprio 1
	s_waitcnt lgkmcnt(0)
	v_mfma_f32_16x16x32_bf16 v[124:127], v[144:147], v[182:185], v[124:127]
	v_mfma_f32_16x16x32_bf16 v[120:123], v[158:161], v[182:185], v[120:123]
	v_mfma_f32_16x16x32_bf16 v[112:115], v[144:147], v[192:195], v[112:115]
	v_mfma_f32_16x16x32_bf16 v[104:107], v[158:161], v[192:195], v[104:107]
	v_mfma_f32_16x16x32_bf16 v[96:99], v[144:147], v[200:203], v[96:99]
	v_mfma_f32_16x16x32_bf16 v[88:91], v[158:161], v[200:203], v[88:91]
	v_mfma_f32_16x16x32_bf16 v[80:83], v[144:147], v[208:211], v[80:83]
	v_mfma_f32_16x16x32_bf16 v[72:75], v[158:161], v[208:211], v[72:75]
	v_mfma_f32_16x16x32_bf16 v[124:127], v[154:157], v[188:191], v[124:127]
	v_mfma_f32_16x16x32_bf16 v[120:123], v[162:165], v[188:191], v[120:123]
	v_mfma_f32_16x16x32_bf16 v[112:115], v[154:157], v[196:199], v[112:115]
	v_mfma_f32_16x16x32_bf16 v[104:107], v[162:165], v[196:199], v[104:107]
	v_mfma_f32_16x16x32_bf16 v[96:99], v[154:157], v[204:207], v[96:99]
	v_mfma_f32_16x16x32_bf16 v[88:91], v[162:165], v[204:207], v[88:91]
	v_mfma_f32_16x16x32_bf16 v[80:83], v[154:157], v[212:215], v[80:83]
	v_mfma_f32_16x16x32_bf16 v[72:75], v[162:165], v[212:215], v[72:75]
	v_mfma_f32_16x16x32_bf16 v[116:119], v[166:169], v[182:185], v[116:119]
	v_mfma_f32_16x16x32_bf16 v[108:111], v[174:177], v[182:185], v[108:111]
	v_mfma_f32_16x16x32_bf16 v[100:103], v[166:169], v[192:195], v[100:103]
	v_mfma_f32_16x16x32_bf16 v[92:95], v[174:177], v[192:195], v[92:95]
	v_mfma_f32_16x16x32_bf16 v[84:87], v[166:169], v[200:203], v[84:87]
	v_mfma_f32_16x16x32_bf16 v[76:79], v[174:177], v[200:203], v[76:79]
	v_mfma_f32_16x16x32_bf16 v[68:71], v[166:169], v[208:211], v[68:71]
	v_mfma_f32_16x16x32_bf16 v[64:67], v[174:177], v[208:211], v[64:67]
	v_mfma_f32_16x16x32_bf16 v[116:119], v[170:173], v[188:191], v[116:119]
	v_mfma_f32_16x16x32_bf16 v[108:111], v[178:181], v[188:191], v[108:111]
	v_mfma_f32_16x16x32_bf16 v[100:103], v[170:173], v[196:199], v[100:103]
	v_mfma_f32_16x16x32_bf16 v[92:95], v[178:181], v[196:199], v[92:95]
	v_mfma_f32_16x16x32_bf16 v[84:87], v[170:173], v[204:207], v[84:87]
	v_mfma_f32_16x16x32_bf16 v[76:79], v[178:181], v[204:207], v[76:79]
	v_mfma_f32_16x16x32_bf16 v[68:71], v[170:173], v[212:215], v[68:71]
	v_mfma_f32_16x16x32_bf16 v[64:67], v[178:181], v[212:215], v[64:67]
	s_setprio 0
	s_barrier
	s_add_u32 s98, s30, s14
	s_addc_u32 s99, s31, s15
	s_add_u32 s100, s34, s14
	s_addc_u32 s101, s35, s15
	s_add_i32 s54, s43, s1
	s_mov_b32 m0, s54
	ds_read_b128 v[182:185], v153 offset:16384
	ds_read_b128 v[188:191], v153 offset:17408
	ds_read_b128 v[192:195], v153 offset:18432
	ds_read_b128 v[196:199], v153 offset:19456
	ds_read_b128 v[200:203], v153 offset:20480
	ds_read_b128 v[204:207], v153 offset:21504
	ds_read_b128 v[208:211], v153 offset:22528
	ds_read_b128 v[212:215], v153 offset:23552
	global_load_lds_dwordx4 v130, s[30:31]
	s_add_i32 m0, s54, 0x2000
	s_add_u32 s54, s30, 0x200000
	s_addc_u32 s55, s31, 0
	s_add_i32 s56, s44, s1
	global_load_lds_dwordx4 v134, s[30:31]
	s_mov_b32 m0, s56
	s_nop 0
	global_load_lds_dwordx4 v130, s[54:55]
	s_add_i32 m0, s56, 0x2000
	s_nop 0
	global_load_lds_dwordx4 v134, s[54:55]
	s_mov_b32 m0, s27
	s_nop 0
	global_load_lds_dwordx4 v128, s[34:35]
	s_mov_b32 m0, s36
	s_nop 0
	global_load_lds_dwordx4 v132, s[34:35]
	s_waitcnt vmcnt(8)
	s_waitcnt lgkmcnt(0)
	s_barrier
	s_setprio 1
	s_waitcnt lgkmcnt(0)
	v_mfma_f32_16x16x32_bf16 v[60:63], v[144:147], v[182:185], v[60:63]
	v_mfma_f32_16x16x32_bf16 v[56:59], v[158:161], v[182:185], v[56:59]
	v_mfma_f32_16x16x32_bf16 v[48:51], v[144:147], v[192:195], v[48:51]
	v_mfma_f32_16x16x32_bf16 v[40:43], v[158:161], v[192:195], v[40:43]
	v_mfma_f32_16x16x32_bf16 v[32:35], v[144:147], v[200:203], v[32:35]
	v_mfma_f32_16x16x32_bf16 v[24:27], v[158:161], v[200:203], v[24:27]
	v_mfma_f32_16x16x32_bf16 v[16:19], v[144:147], v[208:211], v[16:19]
	v_mfma_f32_16x16x32_bf16 v[8:11], v[158:161], v[208:211], v[8:11]
	v_mfma_f32_16x16x32_bf16 v[60:63], v[154:157], v[188:191], v[60:63]
	v_mfma_f32_16x16x32_bf16 v[56:59], v[162:165], v[188:191], v[56:59]
	v_mfma_f32_16x16x32_bf16 v[48:51], v[154:157], v[196:199], v[48:51]
	v_mfma_f32_16x16x32_bf16 v[40:43], v[162:165], v[196:199], v[40:43]
	v_mfma_f32_16x16x32_bf16 v[32:35], v[154:157], v[204:207], v[32:35]
	v_mfma_f32_16x16x32_bf16 v[24:27], v[162:165], v[204:207], v[24:27]
	v_mfma_f32_16x16x32_bf16 v[16:19], v[154:157], v[212:215], v[16:19]
	v_mfma_f32_16x16x32_bf16 v[8:11], v[162:165], v[212:215], v[8:11]
	v_mfma_f32_16x16x32_bf16 v[52:55], v[166:169], v[182:185], v[52:55]
	v_mfma_f32_16x16x32_bf16 v[44:47], v[174:177], v[182:185], v[44:47]
	v_mfma_f32_16x16x32_bf16 v[36:39], v[166:169], v[192:195], v[36:39]
	v_mfma_f32_16x16x32_bf16 v[28:31], v[174:177], v[192:195], v[28:31]
	v_mfma_f32_16x16x32_bf16 v[20:23], v[166:169], v[200:203], v[20:23]
	v_mfma_f32_16x16x32_bf16 v[12:15], v[174:177], v[200:203], v[12:15]
	v_mfma_f32_16x16x32_bf16 v[4:7], v[166:169], v[208:211], v[4:7]
	v_mfma_f32_16x16x32_bf16 v[0:3], v[174:177], v[208:211], v[0:3]
	v_mfma_f32_16x16x32_bf16 v[52:55], v[170:173], v[188:191], v[52:55]
	v_mfma_f32_16x16x32_bf16 v[44:47], v[178:181], v[188:191], v[44:47]
	v_mfma_f32_16x16x32_bf16 v[36:39], v[170:173], v[196:199], v[36:39]
	v_mfma_f32_16x16x32_bf16 v[28:31], v[178:181], v[196:199], v[28:31]
	v_mfma_f32_16x16x32_bf16 v[20:23], v[170:173], v[204:207], v[20:23]
	v_mfma_f32_16x16x32_bf16 v[12:15], v[178:181], v[204:207], v[12:15]
	v_mfma_f32_16x16x32_bf16 v[4:7], v[170:173], v[212:215], v[4:7]
	v_mfma_f32_16x16x32_bf16 v[0:3], v[178:181], v[212:215], v[0:3]
	s_setprio 0
	s_barrier
; #define PG8_STAGE(bufoff, gbase, voff) do { _Pragma("unroll") for (int _i = 0; _i < 2; ++_i) \
;         __builtin_amdgcn_global_load_lds((const unsigned*)((const char*)(gbase) + (voff)[_i]), (PG8_LAS unsigned*)(lds + (bufoff) + ldsw + _i * 8192), 16, 0, 0); } while (0)
; #define PG8_LDA(dst, b, h) do { _Pragma("unroll") for (int m = 0; m < 4; ++m) _Pragma("unroll") for (int k = 0; k < 2; ++k) dst[m][k] = *(const PG8_LAS bf16x8*)(lds + PG8_SA(b, h) + aoff + m * 2048 + k * 1024); } while (0)
; #define PG8_LDB(dst, b, h) do { _Pragma("unroll") for (int n = 0; n < 2; ++n) _Pragma("unroll") for (int k = 0; k < 2; ++k) dst[n][k] = *(const PG8_LAS bf16x8*)(lds + PG8_SB(b, h) + boff + n * 2048 + k * 1024); } while (0)
; #define PG8_MMA(ai, bj, At, Bt) do { __builtin_amdgcn_s_setprio(1); _Pragma("unroll") for (int m = 0; m < 4; ++m) _Pragma("unroll") for (int n = 0; n < 2; ++n) _Pragma("unroll") for (int k = 0; k < 2; ++k) \
;         acc[ai][bj][m][n] = __builtin_amdgcn_mfma_f32_16x16x32_bf16(Bt[n][k], At[m][k], acc[ai][bj][m][n], 0, 0, 0); __builtin_amdgcn_s_setprio(0); } while (0)
; #define PG8_WAIT_V(n) asm volatile("s_waitcnt vmcnt(" #n ")" ::: "memory")
; #define PG8_WAIT_L(n) asm volatile("s_waitcnt lgkmcnt(" #n ")" ::: "memory")
; #define PG8_BAR __builtin_amdgcn_s_barrier()
; #define PG8_SCHED __builtin_amdgcn_sched_barrier(0)
; template <class Epi, class Sched, bool ALIGN_EPI = false, bool SP2 = false>
; __device__ __forceinline__ void gemm_phase(PG8_LAS unsigned char* lds, const Gemm g, const Sched& S, const Epi& E) {
;     ...
;             PG8_LDB(B0, 1, 0); PG8_LDB(B1, 1, 1); PG8_SCHED; PG8_LDA(At, 1, 0); PG8_STAGE(PG8_SA(0, 1), a2 + hstep, voffA);
;             PG8_WAIT_V(8); PG8_WAIT_L(0); PG8_BAR; PG8_MMA(0, 0, At, B0); PG8_MMA(0, 1, At, B1); PG8_BAR; PG8_SCHED;
;             PG8_LDA(At, 1, 1); PG8_STAGE(PG8_SB(1, 0), b3, voffB); PG8_STAGE(PG8_SB(1, 1), b3 + hstep, voffB); PG8_STAGE(PG8_SA(1, 0), a3, voffA);
;             PG8_WAIT_V(8); PG8_WAIT_L(0); PG8_BAR; PG8_MMA(1, 0, At, B0); PG8_MMA(1, 1, At, B1); PG8_BAR; PG8_SCHED;
;     ...
;         if constexpr (ALIGN_EPI) { if (wr == 0) PG8_BAR; }
	s_add_i32 s54, 0, 0x18000
	s_add_i32 s55, 0, 0x1c000
	v_add_u32_e32 v162, s54, v150
	v_add_u32_e32 v178, s55, v150
	ds_read_b128 v[144:147], v162
	ds_read_b128 v[154:157], v162 offset:1024
	ds_read_b128 v[158:161], v162 offset:2048
	ds_read_b128 v[162:165], v162 offset:3072
	ds_read_b128 v[166:169], v178
	ds_read_b128 v[170:173], v178 offset:1024
	ds_read_b128 v[174:177], v178 offset:2048
	ds_read_b128 v[178:181], v178 offset:3072
	s_add_u32 s34, s34, 0x200000
	s_addc_u32 s35, s35, 0
	s_mov_b32 m0, s37
	ds_read_b128 v[182:185], v153 offset:32768
	ds_read_b128 v[188:191], v153 offset:33792
	ds_read_b128 v[192:195], v153 offset:34816
	ds_read_b128 v[196:199], v153 offset:35840
	ds_read_b128 v[200:203], v153 offset:36864
	ds_read_b128 v[204:207], v153 offset:37888
	ds_read_b128 v[208:211], v153 offset:38912
	ds_read_b128 v[212:215], v153 offset:39936
	global_load_lds_dwordx4 v128, s[34:35]
	s_mov_b32 m0, s38
	s_nop 0
	global_load_lds_dwordx4 v132, s[34:35]
	s_waitcnt vmcnt(8)
	s_waitcnt lgkmcnt(0)
	s_barrier
	s_setprio 1
	s_waitcnt lgkmcnt(0)
	v_mfma_f32_16x16x32_bf16 v[124:127], v[144:147], v[182:185], v[124:127]
	v_mfma_f32_16x16x32_bf16 v[120:123], v[158:161], v[182:185], v[120:123]
	v_mfma_f32_16x16x32_bf16 v[112:115], v[144:147], v[192:195], v[112:115]
	v_mfma_f32_16x16x32_bf16 v[104:107], v[158:161], v[192:195], v[104:107]
	v_mfma_f32_16x16x32_bf16 v[96:99], v[144:147], v[200:203], v[96:99]
	v_mfma_f32_16x16x32_bf16 v[88:91], v[158:161], v[200:203], v[88:91]
	v_mfma_f32_16x16x32_bf16 v[80:83], v[144:147], v[208:211], v[80:83]
	v_mfma_f32_16x16x32_bf16 v[72:75], v[158:161], v[208:211], v[72:75]
	v_mfma_f32_16x16x32_bf16 v[124:127], v[154:157], v[188:191], v[124:127]
	v_mfma_f32_16x16x32_bf16 v[120:123], v[162:165], v[188:191], v[120:123]
	v_mfma_f32_16x16x32_bf16 v[112:115], v[154:157], v[196:199], v[112:115]
	v_mfma_f32_16x16x32_bf16 v[104:107], v[162:165], v[196:199], v[104:107]
	v_mfma_f32_16x16x32_bf16 v[96:99], v[154:157], v[204:207], v[96:99]
	v_mfma_f32_16x16x32_bf16 v[88:91], v[162:165], v[204:207], v[88:91]
	v_mfma_f32_16x16x32_bf16 v[80:83], v[154:157], v[212:215], v[80:83]
	v_mfma_f32_16x16x32_bf16 v[72:75], v[162:165], v[212:215], v[72:75]
	v_mfma_f32_16x16x32_bf16 v[116:119], v[166:169], v[182:185], v[116:119]
	v_mfma_f32_16x16x32_bf16 v[108:111], v[174:177], v[182:185], v[108:111]
	v_mfma_f32_16x16x32_bf16 v[100:103], v[166:169], v[192:195], v[100:103]
	v_mfma_f32_16x16x32_bf16 v[92:95], v[174:177], v[192:195], v[92:95]
	v_mfma_f32_16x16x32_bf16 v[84:87], v[166:169], v[200:203], v[84:87]
	v_mfma_f32_16x16x32_bf16 v[76:79], v[174:177], v[200:203], v[76:79]
	v_mfma_f32_16x16x32_bf16 v[68:71], v[166:169], v[208:211], v[68:71]
	v_mfma_f32_16x16x32_bf16 v[64:67], v[174:177], v[208:211], v[64:67]
	v_mfma_f32_16x16x32_bf16 v[116:119], v[170:173], v[188:191], v[116:119]
	v_mfma_f32_16x16x32_bf16 v[108:111], v[178:181], v[188:191], v[108:111]
	v_mfma_f32_16x16x32_bf16 v[100:103], v[170:173], v[196:199], v[100:103]
	v_mfma_f32_16x16x32_bf16 v[92:95], v[178:181], v[196:199], v[92:95]
	v_mfma_f32_16x16x32_bf16 v[84:87], v[170:173], v[204:207], v[84:87]
	v_mfma_f32_16x16x32_bf16 v[76:79], v[178:181], v[204:207], v[76:79]
	v_mfma_f32_16x16x32_bf16 v[68:71], v[170:173], v[212:215], v[68:71]
	v_mfma_f32_16x16x32_bf16 v[64:67], v[178:181], v[212:215], v[64:67]
	s_setprio 0
	s_barrier
	s_add_i32 s34, s54, s1
	s_mov_b32 m0, s34
	ds_read_b128 v[182:185], v153 offset:49152
	ds_read_b128 v[188:191], v153 offset:50176
	ds_read_b128 v[192:195], v153 offset:51200
	ds_read_b128 v[196:199], v153 offset:52224
	ds_read_b128 v[200:203], v153 offset:53248
	ds_read_b128 v[204:207], v153 offset:54272
	ds_read_b128 v[208:211], v153 offset:55296
	ds_read_b128 v[212:215], v153 offset:56320
	global_load_lds_dwordx4 v130, s[98:99]
	s_add_i32 m0, s34, 0x2000
	s_add_u32 s30, s30, 0x200080
	s_addc_u32 s31, s31, 0
	s_add_i32 s34, s55, s1
	global_load_lds_dwordx4 v134, s[98:99]
	s_mov_b32 m0, s34
	s_nop 0
	global_load_lds_dwordx4 v130, s[30:31]
	s_add_i32 m0, s34, 0x2000
	s_nop 0
	global_load_lds_dwordx4 v134, s[30:31]
	s_mov_b32 m0, s40
	s_nop 0
	global_load_lds_dwordx4 v128, s[100:101]
	s_mov_b32 m0, s41
	s_nop 0
	global_load_lds_dwordx4 v132, s[100:101]
	s_waitcnt vmcnt(8)
	s_waitcnt lgkmcnt(0)
	s_barrier
	s_setprio 1
	s_waitcnt lgkmcnt(0)
	v_mfma_f32_16x16x32_bf16 v[60:63], v[144:147], v[182:185], v[60:63]
	v_mfma_f32_16x16x32_bf16 v[56:59], v[158:161], v[182:185], v[56:59]
	v_mfma_f32_16x16x32_bf16 v[48:51], v[144:147], v[192:195], v[48:51]
	v_mfma_f32_16x16x32_bf16 v[40:43], v[158:161], v[192:195], v[40:43]
	v_mfma_f32_16x16x32_bf16 v[32:35], v[144:147], v[200:203], v[32:35]
	v_mfma_f32_16x16x32_bf16 v[24:27], v[158:161], v[200:203], v[24:27]
	v_mfma_f32_16x16x32_bf16 v[16:19], v[144:147], v[208:211], v[16:19]
	v_mfma_f32_16x16x32_bf16 v[8:11], v[158:161], v[208:211], v[8:11]
	v_mfma_f32_16x16x32_bf16 v[60:63], v[154:157], v[188:191], v[60:63]
	v_mfma_f32_16x16x32_bf16 v[56:59], v[162:165], v[188:191], v[56:59]
	v_mfma_f32_16x16x32_bf16 v[48:51], v[154:157], v[196:199], v[48:51]
	v_mfma_f32_16x16x32_bf16 v[40:43], v[162:165], v[196:199], v[40:43]
	v_mfma_f32_16x16x32_bf16 v[32:35], v[154:157], v[204:207], v[32:35]
	v_mfma_f32_16x16x32_bf16 v[24:27], v[162:165], v[204:207], v[24:27]
	v_mfma_f32_16x16x32_bf16 v[16:19], v[154:157], v[212:215], v[16:19]
	v_mfma_f32_16x16x32_bf16 v[8:11], v[162:165], v[212:215], v[8:11]
	v_mfma_f32_16x16x32_bf16 v[52:55], v[166:169], v[182:185], v[52:55]
	v_mfma_f32_16x16x32_bf16 v[44:47], v[174:177], v[182:185], v[44:47]
	v_mfma_f32_16x16x32_bf16 v[36:39], v[166:169], v[192:195], v[36:39]
	v_mfma_f32_16x16x32_bf16 v[28:31], v[174:177], v[192:195], v[28:31]
	v_mfma_f32_16x16x32_bf16 v[20:23], v[166:169], v[200:203], v[20:23]
	v_mfma_f32_16x16x32_bf16 v[12:15], v[174:177], v[200:203], v[12:15]
	v_mfma_f32_16x16x32_bf16 v[4:7], v[166:169], v[208:211], v[4:7]
	v_mfma_f32_16x16x32_bf16 v[0:3], v[174:177], v[208:211], v[0:3]
	v_mfma_f32_16x16x32_bf16 v[52:55], v[170:173], v[188:191], v[52:55]
	v_mfma_f32_16x16x32_bf16 v[44:47], v[178:181], v[188:191], v[44:47]
	v_mfma_f32_16x16x32_bf16 v[36:39], v[170:173], v[196:199], v[36:39]
	v_mfma_f32_16x16x32_bf16 v[28:31], v[178:181], v[196:199], v[28:31]
	v_mfma_f32_16x16x32_bf16 v[20:23], v[170:173], v[204:207], v[20:23]
	v_mfma_f32_16x16x32_bf16 v[12:15], v[178:181], v[204:207], v[12:15]
	v_mfma_f32_16x16x32_bf16 v[4:7], v[170:173], v[212:215], v[4:7]
	v_mfma_f32_16x16x32_bf16 v[0:3], v[178:181], v[212:215], v[0:3]
	s_setprio 0
	s_barrier
	s_add_i32 s51, s51, 2
	s_add_u32 s28, s28, 0x100
	s_addc_u32 s29, s29, 0
	s_add_u32 s49, s49, 0x100
	s_addc_u32 s50, s50, 0
	s_cmpk_gt_u32 s51, 0x7d
	s_cbranch_scc0 .LBB0_803
	s_and_b64 vcc, exec, s[16:17]
	s_cbranch_vccz .LBB0_806
	s_barrier

; #define PG8_STAGE(bufoff, gbase, voff) do { _Pragma("unroll") for (int _i = 0; _i < 2; ++_i) \
;         __builtin_amdgcn_global_load_lds((const unsigned*)((const char*)(gbase) + (voff)[_i]), (PG8_LAS unsigned*)(lds + (bufoff) + ldsw + _i * 8192), 16, 0, 0); } while (0)
; #define PG8_LDA(dst, b, h) do { _Pragma("unroll") for (int m = 0; m < 4; ++m) _Pragma("unroll") for (int k = 0; k < 2; ++k) dst[m][k] = *(const PG8_LAS bf16x8*)(lds + PG8_SA(b, h) + aoff + m * 2048 + k * 1024); } while (0)
; #define PG8_LDB(dst, b, h) do { _Pragma("unroll") for (int n = 0; n < 2; ++n) _Pragma("unroll") for (int k = 0; k < 2; ++k) dst[n][k] = *(const PG8_LAS bf16x8*)(lds + PG8_SB(b, h) + boff + n * 2048 + k * 1024); } while (0)
; #define PG8_MMA(ai, bj, At, Bt) do { __builtin_amdgcn_s_setprio(1); _Pragma("unroll") for (int m = 0; m < 4; ++m) _Pragma("unroll") for (int n = 0; n < 2; ++n) _Pragma("unroll") for (int k = 0; k < 2; ++k) \
;         acc[ai][bj][m][n] = __builtin_amdgcn_mfma_f32_16x16x32_bf16(Bt[n][k], At[m][k], acc[ai][bj][m][n], 0, 0, 0); __builtin_amdgcn_s_setprio(0); } while (0)
; #define PG8_WAIT_V(n) asm volatile("s_waitcnt vmcnt(" #n ")" ::: "memory")
; #define PG8_WAIT_L(n) asm volatile("s_waitcnt lgkmcnt(" #n ")" ::: "memory")
; #define PG8_BAR __builtin_amdgcn_s_barrier()
; template <class Epi, class Sched, bool ALIGN_EPI = false, bool SP2 = false>
; __device__ __forceinline__ void gemm_phase(PG8_LAS unsigned char* lds, const Gemm g, const Sched& S, const Epi& E) {
;     ...
;             const char* a1 = cA + (size_t)(t + 1) * kstep;
;             const char* a2 = last ? nA : cA + (size_t)(t + 2) * kstep; const char* b2 = last ? nB : cB + (size_t)(t + 2) * kstep;
;             const char* a3 = a2 + kstep; const char* b3 = b2 + kstep;
;             if (last && has_next) S.a_ready(nxt);
;             if constexpr (SP2) {
;             PG8_LDB(B0, 0, 0); PG8_LDB(B1, 0, 1); PG8_SCHED; PG8_LDA(At, 0, 0); PG8_STAGE(PG8_SA(1, 1), a1 + hstep, voffA);
;             PG8_WAIT_V(8); PG8_WAIT_L(0); PG8_BAR; PG8_MMA(0, 0, At, B0); PG8_MMA(0, 1, At, B1); PG8_BAR; PG8_SCHED;
;             PG8_LDA(At, 0, 1); PG8_STAGE(PG8_SB(0, 0), b2, voffB); PG8_STAGE(PG8_SB(0, 1), b2 + hstep, voffB); PG8_STAGE(PG8_SA(0, 0), a2, voffA);
;             PG8_WAIT_V(8); PG8_WAIT_L(0); PG8_BAR; PG8_MMA(1, 0, At, B0); PG8_MMA(1, 1, At, B1); PG8_BAR; PG8_SCHED;
.LBB0_921:
	ds_read_b128 v[144:147], v151
	ds_read_b128 v[156:159], v151 offset:1024
	ds_read_b128 v[160:163], v151 offset:2048
	ds_read_b128 v[164:167], v151 offset:3072
	ds_read_b128 v[168:171], v152
	ds_read_b128 v[172:175], v152 offset:1024
	ds_read_b128 v[176:179], v152 offset:2048
	ds_read_b128 v[180:183], v152 offset:3072
	s_add_u32 s30, s28, 0xfff80080
	s_addc_u32 s31, s29, -1
	s_cmp_eq_u32 s53, 28
	s_cselect_b32 s35, s21, s31
	s_cselect_b32 s34, s49, s30
	s_cselect_b32 s31, s19, s52
	s_cselect_b32 s30, s50, s51
	s_add_i32 m0, s27, 0xc000
	ds_read_b128 v[188:191], v153
	ds_read_b128 v[192:195], v153 offset:1024
	ds_read_b128 v[196:199], v153 offset:2048
	ds_read_b128 v[200:203], v153 offset:3072
	ds_read_b128 v[204:207], v153 offset:4096
	ds_read_b128 v[208:211], v153 offset:5120
	ds_read_b128 v[212:215], v153 offset:6144
	ds_read_b128 v[216:219], v153 offset:7168
	global_load_lds_dwordx4 v136, s[28:29]
	s_add_i32 m0, s27, 0xe000
	s_nop 0
	global_load_lds_dwordx4 v138, s[28:29]
	s_waitcnt vmcnt(8)
	s_waitcnt lgkmcnt(0)
	s_barrier
	s_setprio 1
	s_waitcnt lgkmcnt(0)
	v_mfma_f32_16x16x32_bf16 v[124:127], v[144:147], v[188:191], v[124:127]
	v_mfma_f32_16x16x32_bf16 v[120:123], v[160:163], v[188:191], v[120:123]
	v_mfma_f32_16x16x32_bf16 v[108:111], v[144:147], v[196:199], v[108:111]
	v_mfma_f32_16x16x32_bf16 v[104:107], v[160:163], v[196:199], v[104:107]
	v_mfma_f32_16x16x32_bf16 v[92:95], v[144:147], v[204:207], v[92:95]
	v_mfma_f32_16x16x32_bf16 v[88:91], v[160:163], v[204:207], v[88:91]
	v_mfma_f32_16x16x32_bf16 v[76:79], v[144:147], v[212:215], v[76:79]
	v_mfma_f32_16x16x32_bf16 v[72:75], v[160:163], v[212:215], v[72:75]
	v_mfma_f32_16x16x32_bf16 v[124:127], v[156:159], v[192:195], v[124:127]
	v_mfma_f32_16x16x32_bf16 v[120:123], v[164:167], v[192:195], v[120:123]
	v_mfma_f32_16x16x32_bf16 v[108:111], v[156:159], v[200:203], v[108:111]
	v_mfma_f32_16x16x32_bf16 v[104:107], v[164:167], v[200:203], v[104:107]
	v_mfma_f32_16x16x32_bf16 v[92:95], v[156:159], v[208:211], v[92:95]
	v_mfma_f32_16x16x32_bf16 v[88:91], v[164:167], v[208:211], v[88:91]
	v_mfma_f32_16x16x32_bf16 v[76:79], v[156:159], v[216:219], v[76:79]
	v_mfma_f32_16x16x32_bf16 v[72:75], v[164:167], v[216:219], v[72:75]
	v_mfma_f32_16x16x32_bf16 v[116:119], v[168:171], v[188:191], v[116:119]
	v_mfma_f32_16x16x32_bf16 v[112:115], v[176:179], v[188:191], v[112:115]
	v_mfma_f32_16x16x32_bf16 v[100:103], v[168:171], v[196:199], v[100:103]
	v_mfma_f32_16x16x32_bf16 v[96:99], v[176:179], v[196:199], v[96:99]
	v_mfma_f32_16x16x32_bf16 v[84:87], v[168:171], v[204:207], v[84:87]
	v_mfma_f32_16x16x32_bf16 v[80:83], v[176:179], v[204:207], v[80:83]
	v_mfma_f32_16x16x32_bf16 v[68:71], v[168:171], v[212:215], v[68:71]
	v_mfma_f32_16x16x32_bf16 v[64:67], v[176:179], v[212:215], v[64:67]
	v_mfma_f32_16x16x32_bf16 v[116:119], v[172:175], v[192:195], v[116:119]
	v_mfma_f32_16x16x32_bf16 v[112:115], v[180:183], v[192:195], v[112:115]
	v_mfma_f32_16x16x32_bf16 v[100:103], v[172:175], v[200:203], v[100:103]
	v_mfma_f32_16x16x32_bf16 v[96:99], v[180:183], v[200:203], v[96:99]
	v_mfma_f32_16x16x32_bf16 v[84:87], v[172:175], v[208:211], v[84:87]
	v_mfma_f32_16x16x32_bf16 v[80:83], v[180:183], v[208:211], v[80:83]
	v_mfma_f32_16x16x32_bf16 v[68:71], v[172:175], v[216:219], v[68:71]
	v_mfma_f32_16x16x32_bf16 v[64:67], v[180:183], v[216:219], v[64:67]
	s_setprio 0
	s_barrier
	s_add_u32 s98, s30, s14
	s_addc_u32 s99, s31, s15
	s_add_u32 s100, s34, s14
	s_addc_u32 s101, s35, s15
	s_add_i32 s54, s45, s1
	s_mov_b32 m0, s54
	ds_read_b128 v[188:191], v153 offset:16384
	ds_read_b128 v[192:195], v153 offset:17408
	ds_read_b128 v[196:199], v153 offset:18432
	ds_read_b128 v[200:203], v153 offset:19456
	ds_read_b128 v[204:207], v153 offset:20480
	ds_read_b128 v[208:211], v153 offset:21504
	ds_read_b128 v[212:215], v153 offset:22528
	ds_read_b128 v[216:219], v153 offset:23552
	global_load_lds_dwordx4 v130, s[30:31]
	s_add_i32 m0, s54, 0x2000
	s_add_u32 s54, s30, 0x80000
	s_addc_u32 s55, s31, 0
	s_add_i32 s56, s46, s1
	global_load_lds_dwordx4 v134, s[30:31]
	s_mov_b32 m0, s56
	s_nop 0
	global_load_lds_dwordx4 v130, s[54:55]
	s_add_i32 m0, s56, 0x2000
	s_nop 0
	global_load_lds_dwordx4 v134, s[54:55]
	s_mov_b32 m0, s27
	s_nop 0
	global_load_lds_dwordx4 v128, s[34:35]
	s_mov_b32 m0, s36
	s_nop 0
	global_load_lds_dwordx4 v132, s[34:35]
	s_waitcnt vmcnt(8)
	s_waitcnt lgkmcnt(0)
	s_barrier
	s_setprio 1
	s_waitcnt lgkmcnt(0)
	v_mfma_f32_16x16x32_bf16 v[60:63], v[144:147], v[188:191], v[60:63]
	v_mfma_f32_16x16x32_bf16 v[56:59], v[160:163], v[188:191], v[56:59]
	v_mfma_f32_16x16x32_bf16 v[44:47], v[144:147], v[196:199], v[44:47]
	v_mfma_f32_16x16x32_bf16 v[40:43], v[160:163], v[196:199], v[40:43]
	v_mfma_f32_16x16x32_bf16 v[28:31], v[144:147], v[204:207], v[28:31]
	v_mfma_f32_16x16x32_bf16 v[24:27], v[160:163], v[204:207], v[24:27]
	v_mfma_f32_16x16x32_bf16 v[12:15], v[144:147], v[212:215], v[12:15]
	v_mfma_f32_16x16x32_bf16 v[8:11], v[160:163], v[212:215], v[8:11]
	v_mfma_f32_16x16x32_bf16 v[60:63], v[156:159], v[192:195], v[60:63]
	v_mfma_f32_16x16x32_bf16 v[56:59], v[164:167], v[192:195], v[56:59]
	v_mfma_f32_16x16x32_bf16 v[44:47], v[156:159], v[200:203], v[44:47]
	v_mfma_f32_16x16x32_bf16 v[40:43], v[164:167], v[200:203], v[40:43]
	v_mfma_f32_16x16x32_bf16 v[28:31], v[156:159], v[208:211], v[28:31]
	v_mfma_f32_16x16x32_bf16 v[24:27], v[164:167], v[208:211], v[24:27]
	v_mfma_f32_16x16x32_bf16 v[12:15], v[156:159], v[216:219], v[12:15]
	v_mfma_f32_16x16x32_bf16 v[8:11], v[164:167], v[216:219], v[8:11]
	v_mfma_f32_16x16x32_bf16 v[52:55], v[168:171], v[188:191], v[52:55]
	v_mfma_f32_16x16x32_bf16 v[48:51], v[176:179], v[188:191], v[48:51]
	v_mfma_f32_16x16x32_bf16 v[36:39], v[168:171], v[196:199], v[36:39]
	v_mfma_f32_16x16x32_bf16 v[32:35], v[176:179], v[196:199], v[32:35]
	v_mfma_f32_16x16x32_bf16 v[20:23], v[168:171], v[204:207], v[20:23]
	v_mfma_f32_16x16x32_bf16 v[16:19], v[176:179], v[204:207], v[16:19]
	v_mfma_f32_16x16x32_bf16 v[4:7], v[168:171], v[212:215], v[4:7]
	v_mfma_f32_16x16x32_bf16 v[0:3], v[176:179], v[212:215], v[0:3]
	v_mfma_f32_16x16x32_bf16 v[52:55], v[172:175], v[192:195], v[52:55]
	v_mfma_f32_16x16x32_bf16 v[48:51], v[180:183], v[192:195], v[48:51]
	v_mfma_f32_16x16x32_bf16 v[36:39], v[172:175], v[200:203], v[36:39]
	v_mfma_f32_16x16x32_bf16 v[32:35], v[180:183], v[200:203], v[32:35]
	v_mfma_f32_16x16x32_bf16 v[20:23], v[172:175], v[208:211], v[20:23]
	v_mfma_f32_16x16x32_bf16 v[16:19], v[180:183], v[208:211], v[16:19]
	v_mfma_f32_16x16x32_bf16 v[4:7], v[172:175], v[216:219], v[4:7]
	v_mfma_f32_16x16x32_bf16 v[0:3], v[180:183], v[216:219], v[0:3]
	s_setprio 0
	s_barrier
; #define PG8_STAGE(bufoff, gbase, voff) do { _Pragma("unroll") for (int _i = 0; _i < 2; ++_i) \
;         __builtin_amdgcn_global_load_lds((const unsigned*)((const char*)(gbase) + (voff)[_i]), (PG8_LAS unsigned*)(lds + (bufoff) + ldsw + _i * 8192), 16, 0, 0); } while (0)
; #define PG8_LDA(dst, b, h) do { _Pragma("unroll") for (int m = 0; m < 4; ++m) _Pragma("unroll") for (int k = 0; k < 2; ++k) dst[m][k] = *(const PG8_LAS bf16x8*)(lds + PG8_SA(b, h) + aoff + m * 2048 + k * 1024); } while (0)
; #define PG8_LDB(dst, b, h) do { _Pragma("unroll") for (int n = 0; n < 2; ++n) _Pragma("unroll") for (int k = 0; k < 2; ++k) dst[n][k] = *(const PG8_LAS bf16x8*)(lds + PG8_SB(b, h) + boff + n * 2048 + k * 1024); } while (0)
; #define PG8_MMA(ai, bj, At, Bt) do { __builtin_amdgcn_s_setprio(1); _Pragma("unroll") for (int m = 0; m < 4; ++m) _Pragma("unroll") for (int n = 0; n < 2; ++n) _Pragma("unroll") for (int k = 0; k < 2; ++k) \
;         acc[ai][bj][m][n] = __builtin_amdgcn_mfma_f32_16x16x32_bf16(Bt[n][k], At[m][k], acc[ai][bj][m][n], 0, 0, 0); __builtin_amdgcn_s_setprio(0); } while (0)
; #define PG8_WAIT_V(n) asm volatile("s_waitcnt vmcnt(" #n ")" ::: "memory")
; #define PG8_WAIT_L(n) asm volatile("s_waitcnt lgkmcnt(" #n ")" ::: "memory")
; #define PG8_BAR __builtin_amdgcn_s_barrier()
; #define PG8_SCHED __builtin_amdgcn_sched_barrier(0)
; template <class Epi, class Sched, bool ALIGN_EPI = false, bool SP2 = false>
; __device__ __forceinline__ void gemm_phase(PG8_LAS unsigned char* lds, const Gemm g, const Sched& S, const Epi& E) {
;     ...
;             PG8_LDB(B0, 1, 0); PG8_LDB(B1, 1, 1); PG8_SCHED; PG8_LDA(At, 1, 0); PG8_STAGE(PG8_SA(0, 1), a2 + hstep, voffA);
;             PG8_WAIT_V(8); PG8_WAIT_L(0); PG8_BAR; PG8_MMA(0, 0, At, B0); PG8_MMA(0, 1, At, B1); PG8_BAR; PG8_SCHED;
;             PG8_LDA(At, 1, 1); PG8_STAGE(PG8_SB(1, 0), b3, voffB); PG8_STAGE(PG8_SB(1, 1), b3 + hstep, voffB); PG8_STAGE(PG8_SA(1, 0), a3, voffA);
;             PG8_WAIT_V(8); PG8_WAIT_L(0); PG8_BAR; PG8_MMA(1, 0, At, B0); PG8_MMA(1, 1, At, B1); PG8_BAR; PG8_SCHED;
;     ...
;         if constexpr (ALIGN_EPI) { if (wr == 0) PG8_BAR; }
	s_add_i32 s54, 0, 0x18000
	v_add_u32_e32 v155, s54, v150
	s_add_i32 s55, 0, 0x1c000
	ds_read_b128 v[144:147], v155
	ds_read_b128 v[156:159], v155 offset:1024
	ds_read_b128 v[160:163], v155 offset:2048
	ds_read_b128 v[164:167], v155 offset:3072
	v_add_u32_e32 v155, s55, v150
	ds_read_b128 v[168:171], v155
	ds_read_b128 v[172:175], v155 offset:1024
	ds_read_b128 v[176:179], v155 offset:2048
	ds_read_b128 v[180:183], v155 offset:3072
	s_add_u32 s34, s34, 0x80000
	s_addc_u32 s35, s35, 0
	s_mov_b32 m0, s37
	ds_read_b128 v[188:191], v153 offset:32768
	ds_read_b128 v[192:195], v153 offset:33792
	ds_read_b128 v[196:199], v153 offset:34816
	ds_read_b128 v[200:203], v153 offset:35840
	ds_read_b128 v[204:207], v153 offset:36864
	ds_read_b128 v[208:211], v153 offset:37888
	ds_read_b128 v[212:215], v153 offset:38912
	ds_read_b128 v[216:219], v153 offset:39936
	global_load_lds_dwordx4 v128, s[34:35]
	s_mov_b32 m0, s38
	s_nop 0
	global_load_lds_dwordx4 v132, s[34:35]
	s_waitcnt vmcnt(8)
	s_waitcnt lgkmcnt(0)
	s_barrier
	s_setprio 1
	s_waitcnt lgkmcnt(0)
	v_mfma_f32_16x16x32_bf16 v[124:127], v[144:147], v[188:191], v[124:127]
	v_mfma_f32_16x16x32_bf16 v[120:123], v[160:163], v[188:191], v[120:123]
	v_mfma_f32_16x16x32_bf16 v[108:111], v[144:147], v[196:199], v[108:111]
	v_mfma_f32_16x16x32_bf16 v[104:107], v[160:163], v[196:199], v[104:107]
	v_mfma_f32_16x16x32_bf16 v[92:95], v[144:147], v[204:207], v[92:95]
	v_mfma_f32_16x16x32_bf16 v[88:91], v[160:163], v[204:207], v[88:91]
	v_mfma_f32_16x16x32_bf16 v[76:79], v[144:147], v[212:215], v[76:79]
	v_mfma_f32_16x16x32_bf16 v[72:75], v[160:163], v[212:215], v[72:75]
	v_mfma_f32_16x16x32_bf16 v[124:127], v[156:159], v[192:195], v[124:127]
	v_mfma_f32_16x16x32_bf16 v[120:123], v[164:167], v[192:195], v[120:123]
	v_mfma_f32_16x16x32_bf16 v[108:111], v[156:159], v[200:203], v[108:111]
	v_mfma_f32_16x16x32_bf16 v[104:107], v[164:167], v[200:203], v[104:107]
	v_mfma_f32_16x16x32_bf16 v[92:95], v[156:159], v[208:211], v[92:95]
	v_mfma_f32_16x16x32_bf16 v[88:91], v[164:167], v[208:211], v[88:91]
	v_mfma_f32_16x16x32_bf16 v[76:79], v[156:159], v[216:219], v[76:79]
	v_mfma_f32_16x16x32_bf16 v[72:75], v[164:167], v[216:219], v[72:75]
	v_mfma_f32_16x16x32_bf16 v[116:119], v[168:171], v[188:191], v[116:119]
	v_mfma_f32_16x16x32_bf16 v[112:115], v[176:179], v[188:191], v[112:115]
	v_mfma_f32_16x16x32_bf16 v[100:103], v[168:171], v[196:199], v[100:103]
	v_mfma_f32_16x16x32_bf16 v[96:99], v[176:179], v[196:199], v[96:99]
	v_mfma_f32_16x16x32_bf16 v[84:87], v[168:171], v[204:207], v[84:87]
	v_mfma_f32_16x16x32_bf16 v[80:83], v[176:179], v[204:207], v[80:83]
	v_mfma_f32_16x16x32_bf16 v[68:71], v[168:171], v[212:215], v[68:71]
	v_mfma_f32_16x16x32_bf16 v[64:67], v[176:179], v[212:215], v[64:67]
	v_mfma_f32_16x16x32_bf16 v[116:119], v[172:175], v[192:195], v[116:119]
	v_mfma_f32_16x16x32_bf16 v[112:115], v[180:183], v[192:195], v[112:115]
	v_mfma_f32_16x16x32_bf16 v[100:103], v[172:175], v[200:203], v[100:103]
	v_mfma_f32_16x16x32_bf16 v[96:99], v[180:183], v[200:203], v[96:99]
	v_mfma_f32_16x16x32_bf16 v[84:87], v[172:175], v[208:211], v[84:87]
	v_mfma_f32_16x16x32_bf16 v[80:83], v[180:183], v[208:211], v[80:83]
	v_mfma_f32_16x16x32_bf16 v[68:71], v[172:175], v[216:219], v[68:71]
	v_mfma_f32_16x16x32_bf16 v[64:67], v[180:183], v[216:219], v[64:67]
	s_setprio 0
	s_barrier
	s_add_i32 s34, s54, s1
	s_mov_b32 m0, s34
	ds_read_b128 v[188:191], v153 offset:49152
	ds_read_b128 v[192:195], v153 offset:50176
	ds_read_b128 v[196:199], v153 offset:51200
	ds_read_b128 v[200:203], v153 offset:52224
	ds_read_b128 v[204:207], v153 offset:53248
	ds_read_b128 v[208:211], v153 offset:54272
	ds_read_b128 v[212:215], v153 offset:55296
	ds_read_b128 v[216:219], v153 offset:56320
	global_load_lds_dwordx4 v130, s[98:99]
	s_add_i32 m0, s34, 0x2000
	s_add_u32 s30, s30, 0x80080
	s_addc_u32 s31, s31, 0
	s_add_i32 s34, s55, s1
	global_load_lds_dwordx4 v134, s[98:99]
	s_mov_b32 m0, s34
	s_nop 0
	global_load_lds_dwordx4 v130, s[30:31]
	s_add_i32 m0, s34, 0x2000
	s_nop 0
	global_load_lds_dwordx4 v134, s[30:31]
	s_mov_b32 m0, s42
	s_nop 0
	global_load_lds_dwordx4 v128, s[100:101]
	s_mov_b32 m0, s43
	s_nop 0
	global_load_lds_dwordx4 v132, s[100:101]
	s_waitcnt vmcnt(8)
	s_waitcnt lgkmcnt(0)
	s_barrier
	s_setprio 1
	s_waitcnt lgkmcnt(0)
	v_mfma_f32_16x16x32_bf16 v[60:63], v[144:147], v[188:191], v[60:63]
	v_mfma_f32_16x16x32_bf16 v[56:59], v[160:163], v[188:191], v[56:59]
	v_mfma_f32_16x16x32_bf16 v[44:47], v[144:147], v[196:199], v[44:47]
	v_mfma_f32_16x16x32_bf16 v[40:43], v[160:163], v[196:199], v[40:43]
	v_mfma_f32_16x16x32_bf16 v[28:31], v[144:147], v[204:207], v[28:31]
	v_mfma_f32_16x16x32_bf16 v[24:27], v[160:163], v[204:207], v[24:27]
	v_mfma_f32_16x16x32_bf16 v[12:15], v[144:147], v[212:215], v[12:15]
	v_mfma_f32_16x16x32_bf16 v[8:11], v[160:163], v[212:215], v[8:11]
	v_mfma_f32_16x16x32_bf16 v[60:63], v[156:159], v[192:195], v[60:63]
	v_mfma_f32_16x16x32_bf16 v[56:59], v[164:167], v[192:195], v[56:59]
	v_mfma_f32_16x16x32_bf16 v[44:47], v[156:159], v[200:203], v[44:47]
	v_mfma_f32_16x16x32_bf16 v[40:43], v[164:167], v[200:203], v[40:43]
	v_mfma_f32_16x16x32_bf16 v[28:31], v[156:159], v[208:211], v[28:31]
	v_mfma_f32_16x16x32_bf16 v[24:27], v[164:167], v[208:211], v[24:27]
	v_mfma_f32_16x16x32_bf16 v[12:15], v[156:159], v[216:219], v[12:15]
	v_mfma_f32_16x16x32_bf16 v[8:11], v[164:167], v[216:219], v[8:11]
	v_mfma_f32_16x16x32_bf16 v[52:55], v[168:171], v[188:191], v[52:55]
	v_mfma_f32_16x16x32_bf16 v[48:51], v[176:179], v[188:191], v[48:51]
	v_mfma_f32_16x16x32_bf16 v[36:39], v[168:171], v[196:199], v[36:39]
	v_mfma_f32_16x16x32_bf16 v[32:35], v[176:179], v[196:199], v[32:35]
	v_mfma_f32_16x16x32_bf16 v[20:23], v[168:171], v[204:207], v[20:23]
	v_mfma_f32_16x16x32_bf16 v[16:19], v[176:179], v[204:207], v[16:19]
	v_mfma_f32_16x16x32_bf16 v[4:7], v[168:171], v[212:215], v[4:7]
	v_mfma_f32_16x16x32_bf16 v[0:3], v[176:179], v[212:215], v[0:3]
	v_mfma_f32_16x16x32_bf16 v[52:55], v[172:175], v[192:195], v[52:55]
	v_mfma_f32_16x16x32_bf16 v[48:51], v[180:183], v[192:195], v[48:51]
	v_mfma_f32_16x16x32_bf16 v[36:39], v[172:175], v[200:203], v[36:39]
	v_mfma_f32_16x16x32_bf16 v[32:35], v[180:183], v[200:203], v[32:35]
	v_mfma_f32_16x16x32_bf16 v[20:23], v[172:175], v[208:211], v[20:23]
	v_mfma_f32_16x16x32_bf16 v[16:19], v[180:183], v[208:211], v[16:19]
	v_mfma_f32_16x16x32_bf16 v[4:7], v[172:175], v[216:219], v[4:7]
	v_mfma_f32_16x16x32_bf16 v[0:3], v[180:183], v[216:219], v[0:3]
	s_setprio 0
	s_barrier
	s_add_i32 s53, s53, 2
	s_add_u32 s28, s28, 0x100
	s_addc_u32 s29, s29, 0
	s_add_u32 s51, s51, 0x100
	s_addc_u32 s52, s52, 0
	s_cmp_gt_u32 s53, 29
	s_cbranch_scc0 .LBB0_921
	s_and_b64 vcc, exec, s[16:17]
	s_cbranch_vccz .LBB0_924
	s_barrier

; #define PG8_STAGE(bufoff, gbase, voff) do { _Pragma("unroll") for (int _i = 0; _i < 2; ++_i) \
;         __builtin_amdgcn_global_load_lds((const unsigned*)((const char*)(gbase) + (voff)[_i]), (PG8_LAS unsigned*)(lds + (bufoff) + ldsw + _i * 8192), 16, 0, 0); } while (0)
; #define PG8_LDA(dst, b, h) do { _Pragma("unroll") for (int m = 0; m < 4; ++m) _Pragma("unroll") for (int k = 0; k < 2; ++k) dst[m][k] = *(const PG8_LAS bf16x8*)(lds + PG8_SA(b, h) + aoff + m * 2048 + k * 1024); } while (0)
; #define PG8_LDB(dst, b, h) do { _Pragma("unroll") for (int n = 0; n < 2; ++n) _Pragma("unroll") for (int k = 0; k < 2; ++k) dst[n][k] = *(const PG8_LAS bf16x8*)(lds + PG8_SB(b, h) + boff + n * 2048 + k * 1024); } while (0)
; #define PG8_MMA(ai, bj, At, Bt) do { __builtin_amdgcn_s_setprio(1); _Pragma("unroll") for (int m = 0; m < 4; ++m) _Pragma("unroll") for (int n = 0; n < 2; ++n) _Pragma("unroll") for (int k = 0; k < 2; ++k) \
;         acc[ai][bj][m][n] = __builtin_amdgcn_mfma_f32_16x16x32_bf16(Bt[n][k], At[m][k], acc[ai][bj][m][n], 0, 0, 0); __builtin_amdgcn_s_setprio(0); } while (0)
; #define PG8_WAIT_V(n) asm volatile("s_waitcnt vmcnt(" #n ")" ::: "memory")
; #define PG8_WAIT_L(n) asm volatile("s_waitcnt lgkmcnt(" #n ")" ::: "memory")
; #define PG8_BAR __builtin_amdgcn_s_barrier()
; template <class Epi, class Sched, bool ALIGN_EPI = false, bool SP2 = false>
; __device__ __forceinline__ void gemm_phase(PG8_LAS unsigned char* lds, const Gemm g, const Sched& S, const Epi& E) {
;     ...
;             const char* a1 = cA + (size_t)(t + 1) * kstep;
;             const char* a2 = last ? nA : cA + (size_t)(t + 2) * kstep; const char* b2 = last ? nB : cB + (size_t)(t + 2) * kstep;
;             const char* a3 = a2 + kstep; const char* b3 = b2 + kstep;
;             if (last && has_next) S.a_ready(nxt);
;             if constexpr (SP2) {
;             PG8_LDB(B0, 0, 0); PG8_LDB(B1, 0, 1); PG8_SCHED; PG8_LDA(At, 0, 0); PG8_STAGE(PG8_SA(1, 1), a1 + hstep, voffA);
;             PG8_WAIT_V(8); PG8_WAIT_L(0); PG8_BAR; PG8_MMA(0, 0, At, B0); PG8_MMA(0, 1, At, B1); PG8_BAR; PG8_SCHED;
;             PG8_LDA(At, 0, 1); PG8_STAGE(PG8_SB(0, 0), b2, voffB); PG8_STAGE(PG8_SB(0, 1), b2 + hstep, voffB); PG8_STAGE(PG8_SA(0, 0), a2, voffA);
;             PG8_WAIT_V(8); PG8_WAIT_L(0); PG8_BAR; PG8_MMA(1, 0, At, B0); PG8_MMA(1, 1, At, B1); PG8_BAR; PG8_SCHED;
.LBB0_996:
	ds_read_b128 v[144:147], v151
	ds_read_b128 v[154:157], v151 offset:1024
	ds_read_b128 v[158:161], v151 offset:2048
	ds_read_b128 v[162:165], v151 offset:3072
	ds_read_b128 v[166:169], v152
	ds_read_b128 v[170:173], v152 offset:1024
	ds_read_b128 v[174:177], v152 offset:2048
	ds_read_b128 v[178:181], v152 offset:3072
	s_add_u32 s28, s26, 0xffe00080
	s_addc_u32 s29, s27, -1
	s_cmpk_eq_i32 s52, 0x7c
	s_cselect_b32 s31, s19, s29
	s_cselect_b32 s30, s48, s28
	s_cselect_b32 s29, s17, s51
	s_cselect_b32 s28, s49, s50
	s_add_i32 m0, s25, 0xc000
	ds_read_b128 v[182:185], v153
	ds_read_b128 v[186:189], v153 offset:1024
	ds_read_b128 v[190:193], v153 offset:2048
	ds_read_b128 v[194:197], v153 offset:3072
	ds_read_b128 v[198:201], v153 offset:4096
	ds_read_b128 v[202:205], v153 offset:5120
	ds_read_b128 v[206:209], v153 offset:6144
	ds_read_b128 v[210:213], v153 offset:7168
	global_load_lds_dwordx4 v136, s[26:27]
	s_add_i32 m0, s25, 0xe000
	s_nop 0
	global_load_lds_dwordx4 v138, s[26:27]
	s_waitcnt vmcnt(8)
	s_waitcnt lgkmcnt(0)
	s_barrier
	s_setprio 1
	s_waitcnt lgkmcnt(0)
	v_mfma_f32_16x16x32_bf16 v[124:127], v[144:147], v[182:185], v[124:127]
	v_mfma_f32_16x16x32_bf16 v[120:123], v[158:161], v[182:185], v[120:123]
	v_mfma_f32_16x16x32_bf16 v[112:115], v[144:147], v[190:193], v[112:115]
	v_mfma_f32_16x16x32_bf16 v[104:107], v[158:161], v[190:193], v[104:107]
	v_mfma_f32_16x16x32_bf16 v[96:99], v[144:147], v[198:201], v[96:99]
	v_mfma_f32_16x16x32_bf16 v[88:91], v[158:161], v[198:201], v[88:91]
	v_mfma_f32_16x16x32_bf16 v[80:83], v[144:147], v[206:209], v[80:83]
	v_mfma_f32_16x16x32_bf16 v[72:75], v[158:161], v[206:209], v[72:75]
	v_mfma_f32_16x16x32_bf16 v[124:127], v[154:157], v[186:189], v[124:127]
	v_mfma_f32_16x16x32_bf16 v[120:123], v[162:165], v[186:189], v[120:123]
	v_mfma_f32_16x16x32_bf16 v[112:115], v[154:157], v[194:197], v[112:115]
	v_mfma_f32_16x16x32_bf16 v[104:107], v[162:165], v[194:197], v[104:107]
	v_mfma_f32_16x16x32_bf16 v[96:99], v[154:157], v[202:205], v[96:99]
	v_mfma_f32_16x16x32_bf16 v[88:91], v[162:165], v[202:205], v[88:91]
	v_mfma_f32_16x16x32_bf16 v[80:83], v[154:157], v[210:213], v[80:83]
	v_mfma_f32_16x16x32_bf16 v[72:75], v[162:165], v[210:213], v[72:75]
	v_mfma_f32_16x16x32_bf16 v[116:119], v[166:169], v[182:185], v[116:119]
	v_mfma_f32_16x16x32_bf16 v[108:111], v[174:177], v[182:185], v[108:111]
	v_mfma_f32_16x16x32_bf16 v[100:103], v[166:169], v[190:193], v[100:103]
	v_mfma_f32_16x16x32_bf16 v[92:95], v[174:177], v[190:193], v[92:95]
	v_mfma_f32_16x16x32_bf16 v[84:87], v[166:169], v[198:201], v[84:87]
	v_mfma_f32_16x16x32_bf16 v[76:79], v[174:177], v[198:201], v[76:79]
	v_mfma_f32_16x16x32_bf16 v[68:71], v[166:169], v[206:209], v[68:71]
	v_mfma_f32_16x16x32_bf16 v[64:67], v[174:177], v[206:209], v[64:67]
	v_mfma_f32_16x16x32_bf16 v[116:119], v[170:173], v[186:189], v[116:119]
	v_mfma_f32_16x16x32_bf16 v[108:111], v[178:181], v[186:189], v[108:111]
	v_mfma_f32_16x16x32_bf16 v[100:103], v[170:173], v[194:197], v[100:103]
	v_mfma_f32_16x16x32_bf16 v[92:95], v[178:181], v[194:197], v[92:95]
	v_mfma_f32_16x16x32_bf16 v[84:87], v[170:173], v[202:205], v[84:87]
	v_mfma_f32_16x16x32_bf16 v[76:79], v[178:181], v[202:205], v[76:79]
	v_mfma_f32_16x16x32_bf16 v[68:71], v[170:173], v[210:213], v[68:71]
	v_mfma_f32_16x16x32_bf16 v[64:67], v[178:181], v[210:213], v[64:67]
	s_setprio 0
	s_barrier
	s_add_u32 s98, s28, s12
	s_addc_u32 s99, s29, s13
	s_add_u32 s100, s30, s12
	s_addc_u32 s101, s31, s13
	s_add_i32 s53, s44, s36
	s_mov_b32 m0, s53
	ds_read_b128 v[182:185], v153 offset:16384
	ds_read_b128 v[186:189], v153 offset:17408
	ds_read_b128 v[190:193], v153 offset:18432
	ds_read_b128 v[194:197], v153 offset:19456
	ds_read_b128 v[198:201], v153 offset:20480
	ds_read_b128 v[202:205], v153 offset:21504
	ds_read_b128 v[206:209], v153 offset:22528
	ds_read_b128 v[210:213], v153 offset:23552
	global_load_lds_dwordx4 v130, s[28:29]
	s_add_i32 m0, s53, 0x2000
	s_add_u32 s54, s28, 0x200000
	s_addc_u32 s55, s29, 0
	s_add_i32 s53, s45, s36
	global_load_lds_dwordx4 v134, s[28:29]
	s_mov_b32 m0, s53
	s_nop 0
	global_load_lds_dwordx4 v130, s[54:55]
	s_add_i32 m0, s53, 0x2000
	s_nop 0
	global_load_lds_dwordx4 v134, s[54:55]
	s_mov_b32 m0, s25
	s_nop 0
	global_load_lds_dwordx4 v128, s[30:31]
	s_mov_b32 m0, s37
	s_nop 0
	global_load_lds_dwordx4 v132, s[30:31]
	s_waitcnt vmcnt(8)
	s_waitcnt lgkmcnt(0)
	s_barrier
	s_setprio 1
	s_waitcnt lgkmcnt(0)
	v_mfma_f32_16x16x32_bf16 v[60:63], v[144:147], v[182:185], v[60:63]
	v_mfma_f32_16x16x32_bf16 v[56:59], v[158:161], v[182:185], v[56:59]
	v_mfma_f32_16x16x32_bf16 v[48:51], v[144:147], v[190:193], v[48:51]
	v_mfma_f32_16x16x32_bf16 v[40:43], v[158:161], v[190:193], v[40:43]
	v_mfma_f32_16x16x32_bf16 v[32:35], v[144:147], v[198:201], v[32:35]
	v_mfma_f32_16x16x32_bf16 v[24:27], v[158:161], v[198:201], v[24:27]
	v_mfma_f32_16x16x32_bf16 v[16:19], v[144:147], v[206:209], v[16:19]
	v_mfma_f32_16x16x32_bf16 v[8:11], v[158:161], v[206:209], v[8:11]
	v_mfma_f32_16x16x32_bf16 v[60:63], v[154:157], v[186:189], v[60:63]
	v_mfma_f32_16x16x32_bf16 v[56:59], v[162:165], v[186:189], v[56:59]
	v_mfma_f32_16x16x32_bf16 v[48:51], v[154:157], v[194:197], v[48:51]
	v_mfma_f32_16x16x32_bf16 v[40:43], v[162:165], v[194:197], v[40:43]
	v_mfma_f32_16x16x32_bf16 v[32:35], v[154:157], v[202:205], v[32:35]
	v_mfma_f32_16x16x32_bf16 v[24:27], v[162:165], v[202:205], v[24:27]
	v_mfma_f32_16x16x32_bf16 v[16:19], v[154:157], v[210:213], v[16:19]
	v_mfma_f32_16x16x32_bf16 v[8:11], v[162:165], v[210:213], v[8:11]
	v_mfma_f32_16x16x32_bf16 v[52:55], v[166:169], v[182:185], v[52:55]
	v_mfma_f32_16x16x32_bf16 v[44:47], v[174:177], v[182:185], v[44:47]
	v_mfma_f32_16x16x32_bf16 v[36:39], v[166:169], v[190:193], v[36:39]
	v_mfma_f32_16x16x32_bf16 v[28:31], v[174:177], v[190:193], v[28:31]
	v_mfma_f32_16x16x32_bf16 v[20:23], v[166:169], v[198:201], v[20:23]
	v_mfma_f32_16x16x32_bf16 v[12:15], v[174:177], v[198:201], v[12:15]
	v_mfma_f32_16x16x32_bf16 v[4:7], v[166:169], v[206:209], v[4:7]
	v_mfma_f32_16x16x32_bf16 v[0:3], v[174:177], v[206:209], v[0:3]
	v_mfma_f32_16x16x32_bf16 v[52:55], v[170:173], v[186:189], v[52:55]
	v_mfma_f32_16x16x32_bf16 v[44:47], v[178:181], v[186:189], v[44:47]
	v_mfma_f32_16x16x32_bf16 v[36:39], v[170:173], v[194:197], v[36:39]
	v_mfma_f32_16x16x32_bf16 v[28:31], v[178:181], v[194:197], v[28:31]
	v_mfma_f32_16x16x32_bf16 v[20:23], v[170:173], v[202:205], v[20:23]
	v_mfma_f32_16x16x32_bf16 v[12:15], v[178:181], v[202:205], v[12:15]
	v_mfma_f32_16x16x32_bf16 v[4:7], v[170:173], v[210:213], v[4:7]
	v_mfma_f32_16x16x32_bf16 v[0:3], v[178:181], v[210:213], v[0:3]
	s_setprio 0
	s_barrier
; #define PG8_STAGE(bufoff, gbase, voff) do { _Pragma("unroll") for (int _i = 0; _i < 2; ++_i) \
;         __builtin_amdgcn_global_load_lds((const unsigned*)((const char*)(gbase) + (voff)[_i]), (PG8_LAS unsigned*)(lds + (bufoff) + ldsw + _i * 8192), 16, 0, 0); } while (0)
; #define PG8_LDA(dst, b, h) do { _Pragma("unroll") for (int m = 0; m < 4; ++m) _Pragma("unroll") for (int k = 0; k < 2; ++k) dst[m][k] = *(const PG8_LAS bf16x8*)(lds + PG8_SA(b, h) + aoff + m * 2048 + k * 1024); } while (0)
; #define PG8_LDB(dst, b, h) do { _Pragma("unroll") for (int n = 0; n < 2; ++n) _Pragma("unroll") for (int k = 0; k < 2; ++k) dst[n][k] = *(const PG8_LAS bf16x8*)(lds + PG8_SB(b, h) + boff + n * 2048 + k * 1024); } while (0)
; #define PG8_MMA(ai, bj, At, Bt) do { __builtin_amdgcn_s_setprio(1); _Pragma("unroll") for (int m = 0; m < 4; ++m) _Pragma("unroll") for (int n = 0; n < 2; ++n) _Pragma("unroll") for (int k = 0; k < 2; ++k) \
;         acc[ai][bj][m][n] = __builtin_amdgcn_mfma_f32_16x16x32_bf16(Bt[n][k], At[m][k], acc[ai][bj][m][n], 0, 0, 0); __builtin_amdgcn_s_setprio(0); } while (0)
; #define PG8_WAIT_V(n) asm volatile("s_waitcnt vmcnt(" #n ")" ::: "memory")
; #define PG8_WAIT_L(n) asm volatile("s_waitcnt lgkmcnt(" #n ")" ::: "memory")
; #define PG8_BAR __builtin_amdgcn_s_barrier()
; #define PG8_SCHED __builtin_amdgcn_sched_barrier(0)
; template <class Epi, class Sched, bool ALIGN_EPI = false, bool SP2 = false>
; __device__ __forceinline__ void gemm_phase(PG8_LAS unsigned char* lds, const Gemm g, const Sched& S, const Epi& E) {
;     ...
;             PG8_LDB(B0, 1, 0); PG8_LDB(B1, 1, 1); PG8_SCHED; PG8_LDA(At, 1, 0); PG8_STAGE(PG8_SA(0, 1), a2 + hstep, voffA);
;             PG8_WAIT_V(8); PG8_WAIT_L(0); PG8_BAR; PG8_MMA(0, 0, At, B0); PG8_MMA(0, 1, At, B1); PG8_BAR; PG8_SCHED;
;             PG8_LDA(At, 1, 1); PG8_STAGE(PG8_SB(1, 0), b3, voffB); PG8_STAGE(PG8_SB(1, 1), b3 + hstep, voffB); PG8_STAGE(PG8_SA(1, 0), a3, voffA);
;             PG8_WAIT_V(8); PG8_WAIT_L(0); PG8_BAR; PG8_MMA(1, 0, At, B0); PG8_MMA(1, 1, At, B1); PG8_BAR; PG8_SCHED;
;     ...
;         if constexpr (ALIGN_EPI) { if (wr == 0) PG8_BAR; }
	s_add_i32 s53, 0, 0x18000
	s_add_i32 s54, 0, 0x1c000
	v_add_u32_e32 v162, s53, v150
	v_add_u32_e32 v178, s54, v150
	ds_read_b128 v[144:147], v162
	ds_read_b128 v[154:157], v162 offset:1024
	ds_read_b128 v[158:161], v162 offset:2048
	ds_read_b128 v[162:165], v162 offset:3072
	ds_read_b128 v[166:169], v178
	ds_read_b128 v[170:173], v178 offset:1024
	ds_read_b128 v[174:177], v178 offset:2048
	ds_read_b128 v[178:181], v178 offset:3072
	s_add_u32 s30, s30, 0x200000
	s_addc_u32 s31, s31, 0
	s_mov_b32 m0, s38
	ds_read_b128 v[182:185], v153 offset:32768
	ds_read_b128 v[186:189], v153 offset:33792
	ds_read_b128 v[190:193], v153 offset:34816
	ds_read_b128 v[194:197], v153 offset:35840
	ds_read_b128 v[198:201], v153 offset:36864
	ds_read_b128 v[202:205], v153 offset:37888
	ds_read_b128 v[206:209], v153 offset:38912
	ds_read_b128 v[210:213], v153 offset:39936
	global_load_lds_dwordx4 v128, s[30:31]
	s_mov_b32 m0, s39
	s_nop 0
	global_load_lds_dwordx4 v132, s[30:31]
	s_waitcnt vmcnt(8)
	s_waitcnt lgkmcnt(0)
	s_barrier
	s_setprio 1
	s_waitcnt lgkmcnt(0)
	v_mfma_f32_16x16x32_bf16 v[124:127], v[144:147], v[182:185], v[124:127]
	v_mfma_f32_16x16x32_bf16 v[120:123], v[158:161], v[182:185], v[120:123]
	v_mfma_f32_16x16x32_bf16 v[112:115], v[144:147], v[190:193], v[112:115]
	v_mfma_f32_16x16x32_bf16 v[104:107], v[158:161], v[190:193], v[104:107]
	v_mfma_f32_16x16x32_bf16 v[96:99], v[144:147], v[198:201], v[96:99]
	v_mfma_f32_16x16x32_bf16 v[88:91], v[158:161], v[198:201], v[88:91]
	v_mfma_f32_16x16x32_bf16 v[80:83], v[144:147], v[206:209], v[80:83]
	v_mfma_f32_16x16x32_bf16 v[72:75], v[158:161], v[206:209], v[72:75]
	v_mfma_f32_16x16x32_bf16 v[124:127], v[154:157], v[186:189], v[124:127]
	v_mfma_f32_16x16x32_bf16 v[120:123], v[162:165], v[186:189], v[120:123]
	v_mfma_f32_16x16x32_bf16 v[112:115], v[154:157], v[194:197], v[112:115]
	v_mfma_f32_16x16x32_bf16 v[104:107], v[162:165], v[194:197], v[104:107]
	v_mfma_f32_16x16x32_bf16 v[96:99], v[154:157], v[202:205], v[96:99]
	v_mfma_f32_16x16x32_bf16 v[88:91], v[162:165], v[202:205], v[88:91]
	v_mfma_f32_16x16x32_bf16 v[80:83], v[154:157], v[210:213], v[80:83]
	v_mfma_f32_16x16x32_bf16 v[72:75], v[162:165], v[210:213], v[72:75]
	v_mfma_f32_16x16x32_bf16 v[116:119], v[166:169], v[182:185], v[116:119]
	v_mfma_f32_16x16x32_bf16 v[108:111], v[174:177], v[182:185], v[108:111]
	v_mfma_f32_16x16x32_bf16 v[100:103], v[166:169], v[190:193], v[100:103]
	v_mfma_f32_16x16x32_bf16 v[92:95], v[174:177], v[190:193], v[92:95]
	v_mfma_f32_16x16x32_bf16 v[84:87], v[166:169], v[198:201], v[84:87]
	v_mfma_f32_16x16x32_bf16 v[76:79], v[174:177], v[198:201], v[76:79]
	v_mfma_f32_16x16x32_bf16 v[68:71], v[166:169], v[206:209], v[68:71]
	v_mfma_f32_16x16x32_bf16 v[64:67], v[174:177], v[206:209], v[64:67]
	v_mfma_f32_16x16x32_bf16 v[116:119], v[170:173], v[186:189], v[116:119]
	v_mfma_f32_16x16x32_bf16 v[108:111], v[178:181], v[186:189], v[108:111]
	v_mfma_f32_16x16x32_bf16 v[100:103], v[170:173], v[194:197], v[100:103]
	v_mfma_f32_16x16x32_bf16 v[92:95], v[178:181], v[194:197], v[92:95]
	v_mfma_f32_16x16x32_bf16 v[84:87], v[170:173], v[202:205], v[84:87]
	v_mfma_f32_16x16x32_bf16 v[76:79], v[178:181], v[202:205], v[76:79]
	v_mfma_f32_16x16x32_bf16 v[68:71], v[170:173], v[210:213], v[68:71]
	v_mfma_f32_16x16x32_bf16 v[64:67], v[178:181], v[210:213], v[64:67]
	s_setprio 0
	s_barrier
	s_add_i32 s30, s53, s36
	s_mov_b32 m0, s30
	ds_read_b128 v[182:185], v153 offset:49152
	ds_read_b128 v[186:189], v153 offset:50176
	ds_read_b128 v[190:193], v153 offset:51200
	ds_read_b128 v[194:197], v153 offset:52224
	ds_read_b128 v[198:201], v153 offset:53248
	ds_read_b128 v[202:205], v153 offset:54272
	ds_read_b128 v[206:209], v153 offset:55296
	ds_read_b128 v[210:213], v153 offset:56320
	global_load_lds_dwordx4 v130, s[98:99]
	s_add_i32 m0, s30, 0x2000
	s_add_u32 s28, s28, 0x200080
	s_addc_u32 s29, s29, 0
	s_add_i32 s30, s54, s36
	global_load_lds_dwordx4 v134, s[98:99]
	s_mov_b32 m0, s30
	s_nop 0
	global_load_lds_dwordx4 v130, s[28:29]
	s_add_i32 m0, s30, 0x2000
	s_nop 0
	global_load_lds_dwordx4 v134, s[28:29]
	s_mov_b32 m0, s41
	s_nop 0
	global_load_lds_dwordx4 v128, s[100:101]
	s_mov_b32 m0, s42
	s_nop 0
	global_load_lds_dwordx4 v132, s[100:101]
	s_waitcnt vmcnt(8)
	s_waitcnt lgkmcnt(0)
	s_barrier
	s_setprio 1
	s_waitcnt lgkmcnt(0)
	v_mfma_f32_16x16x32_bf16 v[60:63], v[144:147], v[182:185], v[60:63]
	v_mfma_f32_16x16x32_bf16 v[56:59], v[158:161], v[182:185], v[56:59]
	v_mfma_f32_16x16x32_bf16 v[48:51], v[144:147], v[190:193], v[48:51]
	v_mfma_f32_16x16x32_bf16 v[40:43], v[158:161], v[190:193], v[40:43]
	v_mfma_f32_16x16x32_bf16 v[32:35], v[144:147], v[198:201], v[32:35]
	v_mfma_f32_16x16x32_bf16 v[24:27], v[158:161], v[198:201], v[24:27]
	v_mfma_f32_16x16x32_bf16 v[16:19], v[144:147], v[206:209], v[16:19]
	v_mfma_f32_16x16x32_bf16 v[8:11], v[158:161], v[206:209], v[8:11]
	v_mfma_f32_16x16x32_bf16 v[60:63], v[154:157], v[186:189], v[60:63]
	v_mfma_f32_16x16x32_bf16 v[56:59], v[162:165], v[186:189], v[56:59]
	v_mfma_f32_16x16x32_bf16 v[48:51], v[154:157], v[194:197], v[48:51]
	v_mfma_f32_16x16x32_bf16 v[40:43], v[162:165], v[194:197], v[40:43]
	v_mfma_f32_16x16x32_bf16 v[32:35], v[154:157], v[202:205], v[32:35]
	v_mfma_f32_16x16x32_bf16 v[24:27], v[162:165], v[202:205], v[24:27]
	v_mfma_f32_16x16x32_bf16 v[16:19], v[154:157], v[210:213], v[16:19]
	v_mfma_f32_16x16x32_bf16 v[8:11], v[162:165], v[210:213], v[8:11]
	v_mfma_f32_16x16x32_bf16 v[52:55], v[166:169], v[182:185], v[52:55]
	v_mfma_f32_16x16x32_bf16 v[44:47], v[174:177], v[182:185], v[44:47]
	v_mfma_f32_16x16x32_bf16 v[36:39], v[166:169], v[190:193], v[36:39]
	v_mfma_f32_16x16x32_bf16 v[28:31], v[174:177], v[190:193], v[28:31]
	v_mfma_f32_16x16x32_bf16 v[20:23], v[166:169], v[198:201], v[20:23]
	v_mfma_f32_16x16x32_bf16 v[12:15], v[174:177], v[198:201], v[12:15]
	v_mfma_f32_16x16x32_bf16 v[4:7], v[166:169], v[206:209], v[4:7]
	v_mfma_f32_16x16x32_bf16 v[0:3], v[174:177], v[206:209], v[0:3]
	v_mfma_f32_16x16x32_bf16 v[52:55], v[170:173], v[186:189], v[52:55]
	v_mfma_f32_16x16x32_bf16 v[44:47], v[178:181], v[186:189], v[44:47]
	v_mfma_f32_16x16x32_bf16 v[36:39], v[170:173], v[194:197], v[36:39]
	v_mfma_f32_16x16x32_bf16 v[28:31], v[178:181], v[194:197], v[28:31]
	v_mfma_f32_16x16x32_bf16 v[20:23], v[170:173], v[202:205], v[20:23]
	v_mfma_f32_16x16x32_bf16 v[12:15], v[178:181], v[202:205], v[12:15]
	v_mfma_f32_16x16x32_bf16 v[4:7], v[170:173], v[210:213], v[4:7]
	v_mfma_f32_16x16x32_bf16 v[0:3], v[178:181], v[210:213], v[0:3]
	s_setprio 0
	s_barrier
	s_add_i32 s52, s52, 2
	s_add_u32 s26, s26, 0x100
	s_addc_u32 s27, s27, 0
	s_add_u32 s50, s50, 0x100
	s_addc_u32 s51, s51, 0
	s_cmpk_gt_u32 s52, 0x7d
	s_cbranch_scc0 .LBB0_996
	s_and_b64 vcc, exec, s[14:15]
	s_cbranch_vccz .LBB0_999
	s_barrier
